# top-k block selection rewritten (8 tokens interleaved, DPP-fused wave max, batched importance reads); weight transpose/convert ring deepened to 6 tiles in flight
# speedup vs baseline: 1.0392x; 1.0027x over previous
; __device__ __forceinline__ void nsa_unit(LAS unsigned char* lds, const Ctx& P, int l, int b, int hkv, int tb) {
;     ...
;         for (int tt = 0; tt < 8; ++tt) { const int tl = 8 * wid + tt;
;             unsigned long long mask;
;             if (qb <= 7) mask = (2ull << qb) - 1ull;
;             else {
;                 const float v = impb[(0 * 64 + tl) * 64 + lane] + impb[(1 * 64 + tl) * 64 + lane] + impb[(2 * 64 + tl) * 64 + lane] + impb[(3 * 64 + tl) * 64 + lane];
;                 float vv = (lane >= 1 && lane <= qb - 2) ? v : -__builtin_inff();
;                 mask = 1ull | (1ull << qb) | (1ull << (qb - 1));
; #pragma unroll
;                 for (int r = 0; r < 5; ++r) { const float mx = wave_max(vv); const unsigned long long bal = __ballot(vv == mx);
.LBB0_361:
	s_cmp_gt_i32 s54, 7
	s_cselect_b64 s[8:9], -1, 0
	s_add_i32 s0, s54, -2
	s_add_i32 s4, s54, -1
	v_cmp_lt_i32_e64 s[14:15], s0, v99
	s_lshl_b64 s[0:1], 1, s54
	s_lshl_b64 s[4:5], 1, s4
	s_or_b64 s[0:1], s[0:1], s[4:5]
	s_or_b32 s0, s0, 1
	s_lshl_b64 s[4:5], 2, s54
	s_add_u32 s24, s4, -1
	s_addc_u32 s25, s5, -1
	s_mov_b32 s4, s24
	s_mov_b32 s5, s25
	v_cmp_eq_u32_e64 s[12:13], 0, v99
	v_cmp_ne_u32_e64 s[16:17], 0, v99
	s_and_b64 vcc, exec, s[8:9]
	s_mov_b64 s[18:19], s[4:5]
	s_mov_b64 s[66:67], s[22:23]
	v_readlane_b32 s44, v255, 47
	s_waitcnt lgkmcnt(0)
	s_barrier
	s_cmp_gt_i32 s54, 7
	s_cbranch_scc1 .Ltk_sel
	s_mov_b64 s[46:47], s[24:25]
	s_mov_b64 s[56:57], s[24:25]
	s_mov_b64 s[58:59], s[24:25]
	s_mov_b64 s[76:77], s[24:25]
	s_mov_b64 s[82:83], s[24:25]
	s_mov_b64 s[86:87], s[24:25]
	s_mov_b64 s[16:17], s[24:25]
	s_mov_b64 s[28:29], s[24:25]
	s_branch .Ltk_write
.Ltk_sel:
	v_lshlrev_b32_e32 v26, 11, v155
	v_lshl_add_u32 v26, v99, 2, v26
	v_add_u32_e32 v27, 0xd000, v26
	v_add_u32_e32 v28, 0x15000, v26
	ds_read_b32 v30, v27 offset:0
	ds_read_b32 v31, v27 offset:16384
	ds_read_b32 v32, v28 offset:0
	ds_read_b32 v33, v28 offset:16384
	ds_read_b32 v34, v27 offset:256
	ds_read_b32 v35, v27 offset:16640
	ds_read_b32 v36, v28 offset:256
	ds_read_b32 v37, v28 offset:16640
	ds_read_b32 v38, v27 offset:512
	ds_read_b32 v39, v27 offset:16896
	ds_read_b32 v40, v28 offset:512
	ds_read_b32 v41, v28 offset:16896
	ds_read_b32 v42, v27 offset:768
	ds_read_b32 v43, v27 offset:17152
	ds_read_b32 v44, v28 offset:768
	ds_read_b32 v45, v28 offset:17152
	ds_read_b32 v46, v27 offset:1024
	ds_read_b32 v47, v27 offset:17408
	ds_read_b32 v48, v28 offset:1024
	ds_read_b32 v49, v28 offset:17408
	ds_read_b32 v50, v27 offset:1280
	ds_read_b32 v51, v27 offset:17664
	ds_read_b32 v52, v28 offset:1280
	ds_read_b32 v53, v28 offset:17664
	ds_read_b32 v54, v27 offset:1536
	ds_read_b32 v55, v27 offset:17920
	ds_read_b32 v56, v28 offset:1536
	ds_read_b32 v57, v28 offset:17920
	ds_read_b32 v58, v27 offset:1792
	ds_read_b32 v59, v27 offset:18176
	ds_read_b32 v60, v28 offset:1792
	ds_read_b32 v61, v28 offset:18176
	s_mov_b64 s[46:47], s[0:1]
	s_mov_b64 s[56:57], s[0:1]
	s_mov_b64 s[58:59], s[0:1]
	s_mov_b64 s[76:77], s[0:1]
	s_mov_b64 s[82:83], s[0:1]
	s_mov_b64 s[86:87], s[0:1]
	s_mov_b64 s[16:17], s[0:1]
	s_mov_b64 s[28:29], s[0:1]
	s_waitcnt lgkmcnt(0)
	v_add_f32_e32 v18, v30, v31
	v_add_f32_e32 v19, v34, v35
	v_add_f32_e32 v20, v38, v39
	v_add_f32_e32 v21, v42, v43
	v_add_f32_e32 v22, v46, v47
	v_add_f32_e32 v23, v50, v51
	v_add_f32_e32 v24, v54, v55
	v_add_f32_e32 v25, v58, v59
	v_add_f32_e32 v18, v18, v32
	v_add_f32_e32 v19, v19, v36
	v_add_f32_e32 v20, v20, v40
	v_add_f32_e32 v21, v21, v44
	v_add_f32_e32 v22, v22, v48
	v_add_f32_e32 v23, v23, v52
	v_add_f32_e32 v24, v24, v56
	v_add_f32_e32 v25, v25, v60
	v_add_f32_e32 v18, v18, v33
	v_add_f32_e32 v19, v19, v37
	v_add_f32_e32 v20, v20, v41
	v_add_f32_e32 v21, v21, v45
	v_add_f32_e32 v22, v22, v49
	v_add_f32_e32 v23, v23, v53
	v_add_f32_e32 v24, v24, v57
	v_add_f32_e32 v25, v25, v61
	v_cndmask_b32_e64 v18, v18, v242, s[14:15]
	v_cndmask_b32_e64 v19, v19, v242, s[14:15]
	v_cndmask_b32_e64 v20, v20, v242, s[14:15]
	v_cndmask_b32_e64 v21, v21, v242, s[14:15]
	v_cndmask_b32_e64 v22, v22, v242, s[14:15]
	v_cndmask_b32_e64 v23, v23, v242, s[14:15]
	v_cndmask_b32_e64 v24, v24, v242, s[14:15]
	v_cndmask_b32_e64 v25, v25, v242, s[14:15]
	v_cndmask_b32_e64 v18, v18, v242, s[12:13]
	v_cndmask_b32_e64 v19, v19, v242, s[12:13]
	v_cndmask_b32_e64 v20, v20, v242, s[12:13]
	v_cndmask_b32_e64 v21, v21, v242, s[12:13]
	v_cndmask_b32_e64 v22, v22, v242, s[12:13]
	v_cndmask_b32_e64 v23, v23, v242, s[12:13]
	v_cndmask_b32_e64 v24, v24, v242, s[12:13]
	v_cndmask_b32_e64 v25, v25, v242, s[12:13]
	v_max_f32_dpp v62, v18, v18 row_ror:8 row_mask:0xf bank_mask:0xf
	v_max_f32_dpp v63, v19, v19 row_ror:8 row_mask:0xf bank_mask:0xf
	v_max_f32_dpp v64, v20, v20 row_ror:8 row_mask:0xf bank_mask:0xf
	v_max_f32_dpp v65, v21, v21 row_ror:8 row_mask:0xf bank_mask:0xf
	v_max_f32_dpp v66, v22, v22 row_ror:8 row_mask:0xf bank_mask:0xf
	v_max_f32_dpp v67, v23, v23 row_ror:8 row_mask:0xf bank_mask:0xf
	v_max_f32_dpp v68, v24, v24 row_ror:8 row_mask:0xf bank_mask:0xf
	v_max_f32_dpp v69, v25, v25 row_ror:8 row_mask:0xf bank_mask:0xf
	v_max_f32_dpp v62, v62, v62 row_ror:4 row_mask:0xf bank_mask:0xf
	v_max_f32_dpp v63, v63, v63 row_ror:4 row_mask:0xf bank_mask:0xf
	v_max_f32_dpp v64, v64, v64 row_ror:4 row_mask:0xf bank_mask:0xf
	v_max_f32_dpp v65, v65, v65 row_ror:4 row_mask:0xf bank_mask:0xf
	v_max_f32_dpp v66, v66, v66 row_ror:4 row_mask:0xf bank_mask:0xf
	v_max_f32_dpp v67, v67, v67 row_ror:4 row_mask:0xf bank_mask:0xf
	v_max_f32_dpp v68, v68, v68 row_ror:4 row_mask:0xf bank_mask:0xf
	v_max_f32_dpp v69, v69, v69 row_ror:4 row_mask:0xf bank_mask:0xf
	v_max_f32_dpp v62, v62, v62 row_ror:2 row_mask:0xf bank_mask:0xf
	v_max_f32_dpp v63, v63, v63 row_ror:2 row_mask:0xf bank_mask:0xf
	v_max_f32_dpp v64, v64, v64 row_ror:2 row_mask:0xf bank_mask:0xf
	v_max_f32_dpp v65, v65, v65 row_ror:2 row_mask:0xf bank_mask:0xf
	v_max_f32_dpp v66, v66, v66 row_ror:2 row_mask:0xf bank_mask:0xf
	v_max_f32_dpp v67, v67, v67 row_ror:2 row_mask:0xf bank_mask:0xf
	v_max_f32_dpp v68, v68, v68 row_ror:2 row_mask:0xf bank_mask:0xf
	v_max_f32_dpp v69, v69, v69 row_ror:2 row_mask:0xf bank_mask:0xf
	v_max_f32_dpp v62, v62, v62 row_ror:1 row_mask:0xf bank_mask:0xf
	v_max_f32_dpp v63, v63, v63 row_ror:1 row_mask:0xf bank_mask:0xf
	v_max_f32_dpp v64, v64, v64 row_ror:1 row_mask:0xf bank_mask:0xf
	v_max_f32_dpp v65, v65, v65 row_ror:1 row_mask:0xf bank_mask:0xf
; __device__ __forceinline__ float wave_max(float v) {
; #pragma unroll
;     for (int o = 8; o >= 1; o >>= 1) v = fmaxf(v, __shfl_xor(v, o));
;     return rows_max(v); }
; __device__ __forceinline__ void nsa_unit(LAS unsigned char* lds, const Ctx& P, int l, int b, int hkv, int tb) {
;     ...
;                 for (int r = 0; r < 5; ++r) { const float mx = wave_max(vv); const unsigned long long bal = __ballot(vv == mx);
;                     const int js = __builtin_ctzll(bal); mask |= 1ull << js; if (lane == js) vv = -__builtin_inff(); }
	v_max_f32_dpp v66, v66, v66 row_ror:1 row_mask:0xf bank_mask:0xf
	v_max_f32_dpp v67, v67, v67 row_ror:1 row_mask:0xf bank_mask:0xf
	v_max_f32_dpp v68, v68, v68 row_ror:1 row_mask:0xf bank_mask:0xf
	v_max_f32_dpp v69, v69, v69 row_ror:1 row_mask:0xf bank_mask:0xf
	v_mov_b32_e32 v70, v62
	v_mov_b32_e32 v71, v63
	v_mov_b32_e32 v72, v64
	v_mov_b32_e32 v73, v65
	v_mov_b32_e32 v74, v66
	v_mov_b32_e32 v75, v67
	v_mov_b32_e32 v76, v68
	v_mov_b32_e32 v77, v69
	v_permlane16_swap_b32_e32 v62, v70
	v_permlane16_swap_b32_e32 v63, v71
	v_permlane16_swap_b32_e32 v64, v72
	v_permlane16_swap_b32_e32 v65, v73
	v_permlane16_swap_b32_e32 v66, v74
	v_permlane16_swap_b32_e32 v67, v75
	v_permlane16_swap_b32_e32 v68, v76
	v_permlane16_swap_b32_e32 v69, v77
	v_max_f32_e32 v62, v62, v70
	v_max_f32_e32 v63, v63, v71
	v_max_f32_e32 v64, v64, v72
	v_max_f32_e32 v65, v65, v73
	v_max_f32_e32 v66, v66, v74
	v_max_f32_e32 v67, v67, v75
	v_max_f32_e32 v68, v68, v76
	v_max_f32_e32 v69, v69, v77
	v_mov_b32_e32 v70, v62
	v_mov_b32_e32 v71, v63
	v_mov_b32_e32 v72, v64
	v_mov_b32_e32 v73, v65
	v_mov_b32_e32 v74, v66
	v_mov_b32_e32 v75, v67
	v_mov_b32_e32 v76, v68
	v_mov_b32_e32 v77, v69
	v_permlane32_swap_b32_e32 v62, v70
	v_permlane32_swap_b32_e32 v63, v71
	v_permlane32_swap_b32_e32 v64, v72
	v_permlane32_swap_b32_e32 v65, v73
	v_permlane32_swap_b32_e32 v66, v74
	v_permlane32_swap_b32_e32 v67, v75
	v_permlane32_swap_b32_e32 v68, v76
	v_permlane32_swap_b32_e32 v69, v77
	v_max_f32_e32 v62, v62, v70
	v_max_f32_e32 v63, v63, v71
	v_max_f32_e32 v64, v64, v72
	v_max_f32_e32 v65, v65, v73
	v_max_f32_e32 v66, v66, v74
	v_max_f32_e32 v67, v67, v75
	v_max_f32_e32 v68, v68, v76
	v_max_f32_e32 v69, v69, v77
	v_cmp_eq_f32_e64 s[4:5], v18, v62
	v_cmp_eq_f32_e64 s[8:9], v19, v63
	s_ff1_i32_b64 s26, s[4:5]
	s_ff1_i32_b64 s27, s[8:9]
	s_lshl_b64 s[18:19], 1, s26
	s_lshl_b64 s[20:21], 1, s27
	s_or_b64 s[46:47], s[46:47], s[18:19]
	s_or_b64 s[56:57], s[56:57], s[20:21]
	v_cmp_ne_u32_e64 s[4:5], s26, v99
	v_cmp_ne_u32_e64 s[8:9], s27, v99
	s_nop 0
	v_cndmask_b32_e64 v18, v242, v18, s[4:5]
	v_cndmask_b32_e64 v19, v242, v19, s[8:9]
	v_cmp_eq_f32_e64 s[4:5], v20, v64
	v_cmp_eq_f32_e64 s[8:9], v21, v65
	s_ff1_i32_b64 s26, s[4:5]
	s_ff1_i32_b64 s27, s[8:9]
	s_lshl_b64 s[18:19], 1, s26
	s_lshl_b64 s[20:21], 1, s27
	s_or_b64 s[58:59], s[58:59], s[18:19]
	s_or_b64 s[76:77], s[76:77], s[20:21]
	v_cmp_ne_u32_e64 s[4:5], s26, v99
	v_cmp_ne_u32_e64 s[8:9], s27, v99
	s_nop 0
	v_cndmask_b32_e64 v20, v242, v20, s[4:5]
	v_cndmask_b32_e64 v21, v242, v21, s[8:9]
	v_cmp_eq_f32_e64 s[4:5], v22, v66
	v_cmp_eq_f32_e64 s[8:9], v23, v67
	s_ff1_i32_b64 s26, s[4:5]
	s_ff1_i32_b64 s27, s[8:9]
	s_lshl_b64 s[18:19], 1, s26
	s_lshl_b64 s[20:21], 1, s27
	s_or_b64 s[82:83], s[82:83], s[18:19]
	s_or_b64 s[86:87], s[86:87], s[20:21]
	v_cmp_ne_u32_e64 s[4:5], s26, v99
	v_cmp_ne_u32_e64 s[8:9], s27, v99
	s_nop 0
	v_cndmask_b32_e64 v22, v242, v22, s[4:5]
	v_cndmask_b32_e64 v23, v242, v23, s[8:9]
	v_cmp_eq_f32_e64 s[4:5], v24, v68
	v_cmp_eq_f32_e64 s[8:9], v25, v69
	s_ff1_i32_b64 s26, s[4:5]
	s_ff1_i32_b64 s27, s[8:9]
	s_lshl_b64 s[18:19], 1, s26
	s_lshl_b64 s[20:21], 1, s27
	s_or_b64 s[16:17], s[16:17], s[18:19]
	s_or_b64 s[28:29], s[28:29], s[20:21]
	v_cmp_ne_u32_e64 s[4:5], s26, v99
	v_cmp_ne_u32_e64 s[8:9], s27, v99
	s_nop 0
	v_cndmask_b32_e64 v24, v242, v24, s[4:5]
	v_cndmask_b32_e64 v25, v242, v25, s[8:9]
	v_max_f32_dpp v62, v18, v18 row_ror:8 row_mask:0xf bank_mask:0xf
	v_max_f32_dpp v63, v19, v19 row_ror:8 row_mask:0xf bank_mask:0xf
	v_max_f32_dpp v64, v20, v20 row_ror:8 row_mask:0xf bank_mask:0xf
	v_max_f32_dpp v65, v21, v21 row_ror:8 row_mask:0xf bank_mask:0xf
	v_max_f32_dpp v66, v22, v22 row_ror:8 row_mask:0xf bank_mask:0xf
	v_max_f32_dpp v67, v23, v23 row_ror:8 row_mask:0xf bank_mask:0xf
	v_max_f32_dpp v68, v24, v24 row_ror:8 row_mask:0xf bank_mask:0xf
	v_max_f32_dpp v69, v25, v25 row_ror:8 row_mask:0xf bank_mask:0xf
	v_max_f32_dpp v62, v62, v62 row_ror:4 row_mask:0xf bank_mask:0xf
	v_max_f32_dpp v63, v63, v63 row_ror:4 row_mask:0xf bank_mask:0xf
	v_max_f32_dpp v64, v64, v64 row_ror:4 row_mask:0xf bank_mask:0xf
	v_max_f32_dpp v65, v65, v65 row_ror:4 row_mask:0xf bank_mask:0xf
	v_max_f32_dpp v66, v66, v66 row_ror:4 row_mask:0xf bank_mask:0xf
	v_max_f32_dpp v67, v67, v67 row_ror:4 row_mask:0xf bank_mask:0xf
	v_max_f32_dpp v68, v68, v68 row_ror:4 row_mask:0xf bank_mask:0xf
	v_max_f32_dpp v69, v69, v69 row_ror:4 row_mask:0xf bank_mask:0xf
	v_max_f32_dpp v62, v62, v62 row_ror:2 row_mask:0xf bank_mask:0xf
	v_max_f32_dpp v63, v63, v63 row_ror:2 row_mask:0xf bank_mask:0xf
	v_max_f32_dpp v64, v64, v64 row_ror:2 row_mask:0xf bank_mask:0xf
	v_max_f32_dpp v65, v65, v65 row_ror:2 row_mask:0xf bank_mask:0xf
	v_max_f32_dpp v66, v66, v66 row_ror:2 row_mask:0xf bank_mask:0xf
	v_max_f32_dpp v67, v67, v67 row_ror:2 row_mask:0xf bank_mask:0xf
	v_max_f32_dpp v68, v68, v68 row_ror:2 row_mask:0xf bank_mask:0xf
	v_max_f32_dpp v69, v69, v69 row_ror:2 row_mask:0xf bank_mask:0xf
	v_max_f32_dpp v62, v62, v62 row_ror:1 row_mask:0xf bank_mask:0xf
	v_max_f32_dpp v63, v63, v63 row_ror:1 row_mask:0xf bank_mask:0xf
	v_max_f32_dpp v64, v64, v64 row_ror:1 row_mask:0xf bank_mask:0xf
	v_max_f32_dpp v65, v65, v65 row_ror:1 row_mask:0xf bank_mask:0xf
	v_max_f32_dpp v66, v66, v66 row_ror:1 row_mask:0xf bank_mask:0xf
	v_max_f32_dpp v67, v67, v67 row_ror:1 row_mask:0xf bank_mask:0xf
	v_max_f32_dpp v68, v68, v68 row_ror:1 row_mask:0xf bank_mask:0xf
	v_max_f32_dpp v69, v69, v69 row_ror:1 row_mask:0xf bank_mask:0xf
	v_mov_b32_e32 v70, v62
	v_mov_b32_e32 v71, v63
	v_mov_b32_e32 v72, v64
	v_mov_b32_e32 v73, v65
	v_mov_b32_e32 v74, v66
	v_mov_b32_e32 v75, v67
; __device__ __forceinline__ float wave_max(float v) {
; #pragma unroll
;     for (int o = 8; o >= 1; o >>= 1) v = fmaxf(v, __shfl_xor(v, o));
;     return rows_max(v); }
; __device__ __forceinline__ void nsa_unit(LAS unsigned char* lds, const Ctx& P, int l, int b, int hkv, int tb) {
;     ...
;                 for (int r = 0; r < 5; ++r) { const float mx = wave_max(vv); const unsigned long long bal = __ballot(vv == mx);
;                     const int js = __builtin_ctzll(bal); mask |= 1ull << js; if (lane == js) vv = -__builtin_inff(); }
	v_mov_b32_e32 v76, v68
	v_mov_b32_e32 v77, v69
	v_permlane16_swap_b32_e32 v62, v70
	v_permlane16_swap_b32_e32 v63, v71
	v_permlane16_swap_b32_e32 v64, v72
	v_permlane16_swap_b32_e32 v65, v73
	v_permlane16_swap_b32_e32 v66, v74
	v_permlane16_swap_b32_e32 v67, v75
	v_permlane16_swap_b32_e32 v68, v76
	v_permlane16_swap_b32_e32 v69, v77
	v_max_f32_e32 v62, v62, v70
	v_max_f32_e32 v63, v63, v71
	v_max_f32_e32 v64, v64, v72
	v_max_f32_e32 v65, v65, v73
	v_max_f32_e32 v66, v66, v74
	v_max_f32_e32 v67, v67, v75
	v_max_f32_e32 v68, v68, v76
	v_max_f32_e32 v69, v69, v77
	v_mov_b32_e32 v70, v62
	v_mov_b32_e32 v71, v63
	v_mov_b32_e32 v72, v64
	v_mov_b32_e32 v73, v65
	v_mov_b32_e32 v74, v66
	v_mov_b32_e32 v75, v67
	v_mov_b32_e32 v76, v68
	v_mov_b32_e32 v77, v69
	v_permlane32_swap_b32_e32 v62, v70
	v_permlane32_swap_b32_e32 v63, v71
	v_permlane32_swap_b32_e32 v64, v72
	v_permlane32_swap_b32_e32 v65, v73
	v_permlane32_swap_b32_e32 v66, v74
	v_permlane32_swap_b32_e32 v67, v75
	v_permlane32_swap_b32_e32 v68, v76
	v_permlane32_swap_b32_e32 v69, v77
	v_max_f32_e32 v62, v62, v70
	v_max_f32_e32 v63, v63, v71
	v_max_f32_e32 v64, v64, v72
	v_max_f32_e32 v65, v65, v73
	v_max_f32_e32 v66, v66, v74
	v_max_f32_e32 v67, v67, v75
	v_max_f32_e32 v68, v68, v76
	v_max_f32_e32 v69, v69, v77
	v_cmp_eq_f32_e64 s[4:5], v18, v62
	v_cmp_eq_f32_e64 s[8:9], v19, v63
	s_ff1_i32_b64 s26, s[4:5]
	s_ff1_i32_b64 s27, s[8:9]
	s_lshl_b64 s[18:19], 1, s26
	s_lshl_b64 s[20:21], 1, s27
	s_or_b64 s[46:47], s[46:47], s[18:19]
	s_or_b64 s[56:57], s[56:57], s[20:21]
	v_cmp_ne_u32_e64 s[4:5], s26, v99
	v_cmp_ne_u32_e64 s[8:9], s27, v99
	s_nop 0
	v_cndmask_b32_e64 v18, v242, v18, s[4:5]
	v_cndmask_b32_e64 v19, v242, v19, s[8:9]
	v_cmp_eq_f32_e64 s[4:5], v20, v64
	v_cmp_eq_f32_e64 s[8:9], v21, v65
	s_ff1_i32_b64 s26, s[4:5]
	s_ff1_i32_b64 s27, s[8:9]
	s_lshl_b64 s[18:19], 1, s26
	s_lshl_b64 s[20:21], 1, s27
	s_or_b64 s[58:59], s[58:59], s[18:19]
	s_or_b64 s[76:77], s[76:77], s[20:21]
	v_cmp_ne_u32_e64 s[4:5], s26, v99
	v_cmp_ne_u32_e64 s[8:9], s27, v99
	s_nop 0
	v_cndmask_b32_e64 v20, v242, v20, s[4:5]
	v_cndmask_b32_e64 v21, v242, v21, s[8:9]
	v_cmp_eq_f32_e64 s[4:5], v22, v66
	v_cmp_eq_f32_e64 s[8:9], v23, v67
	s_ff1_i32_b64 s26, s[4:5]
	s_ff1_i32_b64 s27, s[8:9]
	s_lshl_b64 s[18:19], 1, s26
	s_lshl_b64 s[20:21], 1, s27
	s_or_b64 s[82:83], s[82:83], s[18:19]
	s_or_b64 s[86:87], s[86:87], s[20:21]
	v_cmp_ne_u32_e64 s[4:5], s26, v99
	v_cmp_ne_u32_e64 s[8:9], s27, v99
	s_nop 0
	v_cndmask_b32_e64 v22, v242, v22, s[4:5]
	v_cndmask_b32_e64 v23, v242, v23, s[8:9]
	v_cmp_eq_f32_e64 s[4:5], v24, v68
	v_cmp_eq_f32_e64 s[8:9], v25, v69
	s_ff1_i32_b64 s26, s[4:5]
	s_ff1_i32_b64 s27, s[8:9]
	s_lshl_b64 s[18:19], 1, s26
	s_lshl_b64 s[20:21], 1, s27
	s_or_b64 s[16:17], s[16:17], s[18:19]
	s_or_b64 s[28:29], s[28:29], s[20:21]
	v_cmp_ne_u32_e64 s[4:5], s26, v99
	v_cmp_ne_u32_e64 s[8:9], s27, v99
	s_nop 0
	v_cndmask_b32_e64 v24, v242, v24, s[4:5]
	v_cndmask_b32_e64 v25, v242, v25, s[8:9]
	v_max_f32_dpp v62, v18, v18 row_ror:8 row_mask:0xf bank_mask:0xf
	v_max_f32_dpp v63, v19, v19 row_ror:8 row_mask:0xf bank_mask:0xf
	v_max_f32_dpp v64, v20, v20 row_ror:8 row_mask:0xf bank_mask:0xf
	v_max_f32_dpp v65, v21, v21 row_ror:8 row_mask:0xf bank_mask:0xf
	v_max_f32_dpp v66, v22, v22 row_ror:8 row_mask:0xf bank_mask:0xf
	v_max_f32_dpp v67, v23, v23 row_ror:8 row_mask:0xf bank_mask:0xf
	v_max_f32_dpp v68, v24, v24 row_ror:8 row_mask:0xf bank_mask:0xf
	v_max_f32_dpp v69, v25, v25 row_ror:8 row_mask:0xf bank_mask:0xf
	v_max_f32_dpp v62, v62, v62 row_ror:4 row_mask:0xf bank_mask:0xf
	v_max_f32_dpp v63, v63, v63 row_ror:4 row_mask:0xf bank_mask:0xf
	v_max_f32_dpp v64, v64, v64 row_ror:4 row_mask:0xf bank_mask:0xf
	v_max_f32_dpp v65, v65, v65 row_ror:4 row_mask:0xf bank_mask:0xf
	v_max_f32_dpp v66, v66, v66 row_ror:4 row_mask:0xf bank_mask:0xf
	v_max_f32_dpp v67, v67, v67 row_ror:4 row_mask:0xf bank_mask:0xf
	v_max_f32_dpp v68, v68, v68 row_ror:4 row_mask:0xf bank_mask:0xf
	v_max_f32_dpp v69, v69, v69 row_ror:4 row_mask:0xf bank_mask:0xf
	v_max_f32_dpp v62, v62, v62 row_ror:2 row_mask:0xf bank_mask:0xf
	v_max_f32_dpp v63, v63, v63 row_ror:2 row_mask:0xf bank_mask:0xf
	v_max_f32_dpp v64, v64, v64 row_ror:2 row_mask:0xf bank_mask:0xf
	v_max_f32_dpp v65, v65, v65 row_ror:2 row_mask:0xf bank_mask:0xf
	v_max_f32_dpp v66, v66, v66 row_ror:2 row_mask:0xf bank_mask:0xf
	v_max_f32_dpp v67, v67, v67 row_ror:2 row_mask:0xf bank_mask:0xf
	v_max_f32_dpp v68, v68, v68 row_ror:2 row_mask:0xf bank_mask:0xf
	v_max_f32_dpp v69, v69, v69 row_ror:2 row_mask:0xf bank_mask:0xf
	v_max_f32_dpp v62, v62, v62 row_ror:1 row_mask:0xf bank_mask:0xf
	v_max_f32_dpp v63, v63, v63 row_ror:1 row_mask:0xf bank_mask:0xf
	v_max_f32_dpp v64, v64, v64 row_ror:1 row_mask:0xf bank_mask:0xf
	v_max_f32_dpp v65, v65, v65 row_ror:1 row_mask:0xf bank_mask:0xf
	v_max_f32_dpp v66, v66, v66 row_ror:1 row_mask:0xf bank_mask:0xf
	v_max_f32_dpp v67, v67, v67 row_ror:1 row_mask:0xf bank_mask:0xf
	v_max_f32_dpp v68, v68, v68 row_ror:1 row_mask:0xf bank_mask:0xf
	v_max_f32_dpp v69, v69, v69 row_ror:1 row_mask:0xf bank_mask:0xf
	v_mov_b32_e32 v70, v62
	v_mov_b32_e32 v71, v63
	v_mov_b32_e32 v72, v64
	v_mov_b32_e32 v73, v65
	v_mov_b32_e32 v74, v66
	v_mov_b32_e32 v75, v67
	v_mov_b32_e32 v76, v68
	v_mov_b32_e32 v77, v69
	v_permlane16_swap_b32_e32 v62, v70
	v_permlane16_swap_b32_e32 v63, v71
	v_permlane16_swap_b32_e32 v64, v72
	v_permlane16_swap_b32_e32 v65, v73
	v_permlane16_swap_b32_e32 v66, v74
	v_permlane16_swap_b32_e32 v67, v75
	v_permlane16_swap_b32_e32 v68, v76
	v_permlane16_swap_b32_e32 v69, v77
	v_max_f32_e32 v62, v62, v70
	v_max_f32_e32 v63, v63, v71
	v_max_f32_e32 v64, v64, v72
; __device__ __forceinline__ float wave_max(float v) {
; #pragma unroll
;     for (int o = 8; o >= 1; o >>= 1) v = fmaxf(v, __shfl_xor(v, o));
;     return rows_max(v); }
; __device__ __forceinline__ void nsa_unit(LAS unsigned char* lds, const Ctx& P, int l, int b, int hkv, int tb) {
;     ...
;                 for (int r = 0; r < 5; ++r) { const float mx = wave_max(vv); const unsigned long long bal = __ballot(vv == mx);
;                     const int js = __builtin_ctzll(bal); mask |= 1ull << js; if (lane == js) vv = -__builtin_inff(); }
	v_max_f32_e32 v65, v65, v73
	v_max_f32_e32 v66, v66, v74
	v_max_f32_e32 v67, v67, v75
	v_max_f32_e32 v68, v68, v76
	v_max_f32_e32 v69, v69, v77
	v_mov_b32_e32 v70, v62
	v_mov_b32_e32 v71, v63
	v_mov_b32_e32 v72, v64
	v_mov_b32_e32 v73, v65
	v_mov_b32_e32 v74, v66
	v_mov_b32_e32 v75, v67
	v_mov_b32_e32 v76, v68
	v_mov_b32_e32 v77, v69
	v_permlane32_swap_b32_e32 v62, v70
	v_permlane32_swap_b32_e32 v63, v71
	v_permlane32_swap_b32_e32 v64, v72
	v_permlane32_swap_b32_e32 v65, v73
	v_permlane32_swap_b32_e32 v66, v74
	v_permlane32_swap_b32_e32 v67, v75
	v_permlane32_swap_b32_e32 v68, v76
	v_permlane32_swap_b32_e32 v69, v77
	v_max_f32_e32 v62, v62, v70
	v_max_f32_e32 v63, v63, v71
	v_max_f32_e32 v64, v64, v72
	v_max_f32_e32 v65, v65, v73
	v_max_f32_e32 v66, v66, v74
	v_max_f32_e32 v67, v67, v75
	v_max_f32_e32 v68, v68, v76
	v_max_f32_e32 v69, v69, v77
	v_cmp_eq_f32_e64 s[4:5], v18, v62
	v_cmp_eq_f32_e64 s[8:9], v19, v63
	s_ff1_i32_b64 s26, s[4:5]
	s_ff1_i32_b64 s27, s[8:9]
	s_lshl_b64 s[18:19], 1, s26
	s_lshl_b64 s[20:21], 1, s27
	s_or_b64 s[46:47], s[46:47], s[18:19]
	s_or_b64 s[56:57], s[56:57], s[20:21]
	v_cmp_ne_u32_e64 s[4:5], s26, v99
	v_cmp_ne_u32_e64 s[8:9], s27, v99
	s_nop 0
	v_cndmask_b32_e64 v18, v242, v18, s[4:5]
	v_cndmask_b32_e64 v19, v242, v19, s[8:9]
	v_cmp_eq_f32_e64 s[4:5], v20, v64
	v_cmp_eq_f32_e64 s[8:9], v21, v65
	s_ff1_i32_b64 s26, s[4:5]
	s_ff1_i32_b64 s27, s[8:9]
	s_lshl_b64 s[18:19], 1, s26
	s_lshl_b64 s[20:21], 1, s27
	s_or_b64 s[58:59], s[58:59], s[18:19]
	s_or_b64 s[76:77], s[76:77], s[20:21]
	v_cmp_ne_u32_e64 s[4:5], s26, v99
	v_cmp_ne_u32_e64 s[8:9], s27, v99
	s_nop 0
	v_cndmask_b32_e64 v20, v242, v20, s[4:5]
	v_cndmask_b32_e64 v21, v242, v21, s[8:9]
	v_cmp_eq_f32_e64 s[4:5], v22, v66
	v_cmp_eq_f32_e64 s[8:9], v23, v67
	s_ff1_i32_b64 s26, s[4:5]
	s_ff1_i32_b64 s27, s[8:9]
	s_lshl_b64 s[18:19], 1, s26
	s_lshl_b64 s[20:21], 1, s27
	s_or_b64 s[82:83], s[82:83], s[18:19]
	s_or_b64 s[86:87], s[86:87], s[20:21]
	v_cmp_ne_u32_e64 s[4:5], s26, v99
	v_cmp_ne_u32_e64 s[8:9], s27, v99
	s_nop 0
	v_cndmask_b32_e64 v22, v242, v22, s[4:5]
	v_cndmask_b32_e64 v23, v242, v23, s[8:9]
	v_cmp_eq_f32_e64 s[4:5], v24, v68
	v_cmp_eq_f32_e64 s[8:9], v25, v69
	s_ff1_i32_b64 s26, s[4:5]
	s_ff1_i32_b64 s27, s[8:9]
	s_lshl_b64 s[18:19], 1, s26
	s_lshl_b64 s[20:21], 1, s27
	s_or_b64 s[16:17], s[16:17], s[18:19]
	s_or_b64 s[28:29], s[28:29], s[20:21]
	v_cmp_ne_u32_e64 s[4:5], s26, v99
	v_cmp_ne_u32_e64 s[8:9], s27, v99
	s_nop 0
	v_cndmask_b32_e64 v24, v242, v24, s[4:5]
	v_cndmask_b32_e64 v25, v242, v25, s[8:9]
	v_max_f32_dpp v62, v18, v18 row_ror:8 row_mask:0xf bank_mask:0xf
	v_max_f32_dpp v63, v19, v19 row_ror:8 row_mask:0xf bank_mask:0xf
	v_max_f32_dpp v64, v20, v20 row_ror:8 row_mask:0xf bank_mask:0xf
	v_max_f32_dpp v65, v21, v21 row_ror:8 row_mask:0xf bank_mask:0xf
	v_max_f32_dpp v66, v22, v22 row_ror:8 row_mask:0xf bank_mask:0xf
	v_max_f32_dpp v67, v23, v23 row_ror:8 row_mask:0xf bank_mask:0xf
	v_max_f32_dpp v68, v24, v24 row_ror:8 row_mask:0xf bank_mask:0xf
	v_max_f32_dpp v69, v25, v25 row_ror:8 row_mask:0xf bank_mask:0xf
	v_max_f32_dpp v62, v62, v62 row_ror:4 row_mask:0xf bank_mask:0xf
	v_max_f32_dpp v63, v63, v63 row_ror:4 row_mask:0xf bank_mask:0xf
	v_max_f32_dpp v64, v64, v64 row_ror:4 row_mask:0xf bank_mask:0xf
	v_max_f32_dpp v65, v65, v65 row_ror:4 row_mask:0xf bank_mask:0xf
	v_max_f32_dpp v66, v66, v66 row_ror:4 row_mask:0xf bank_mask:0xf
	v_max_f32_dpp v67, v67, v67 row_ror:4 row_mask:0xf bank_mask:0xf
	v_max_f32_dpp v68, v68, v68 row_ror:4 row_mask:0xf bank_mask:0xf
	v_max_f32_dpp v69, v69, v69 row_ror:4 row_mask:0xf bank_mask:0xf
	v_max_f32_dpp v62, v62, v62 row_ror:2 row_mask:0xf bank_mask:0xf
	v_max_f32_dpp v63, v63, v63 row_ror:2 row_mask:0xf bank_mask:0xf
	v_max_f32_dpp v64, v64, v64 row_ror:2 row_mask:0xf bank_mask:0xf
	v_max_f32_dpp v65, v65, v65 row_ror:2 row_mask:0xf bank_mask:0xf
	v_max_f32_dpp v66, v66, v66 row_ror:2 row_mask:0xf bank_mask:0xf
	v_max_f32_dpp v67, v67, v67 row_ror:2 row_mask:0xf bank_mask:0xf
	v_max_f32_dpp v68, v68, v68 row_ror:2 row_mask:0xf bank_mask:0xf
	v_max_f32_dpp v69, v69, v69 row_ror:2 row_mask:0xf bank_mask:0xf
	v_max_f32_dpp v62, v62, v62 row_ror:1 row_mask:0xf bank_mask:0xf
	v_max_f32_dpp v63, v63, v63 row_ror:1 row_mask:0xf bank_mask:0xf
	v_max_f32_dpp v64, v64, v64 row_ror:1 row_mask:0xf bank_mask:0xf
	v_max_f32_dpp v65, v65, v65 row_ror:1 row_mask:0xf bank_mask:0xf
	v_max_f32_dpp v66, v66, v66 row_ror:1 row_mask:0xf bank_mask:0xf
	v_max_f32_dpp v67, v67, v67 row_ror:1 row_mask:0xf bank_mask:0xf
	v_max_f32_dpp v68, v68, v68 row_ror:1 row_mask:0xf bank_mask:0xf
	v_max_f32_dpp v69, v69, v69 row_ror:1 row_mask:0xf bank_mask:0xf
	v_mov_b32_e32 v70, v62
	v_mov_b32_e32 v71, v63
	v_mov_b32_e32 v72, v64
	v_mov_b32_e32 v73, v65
	v_mov_b32_e32 v74, v66
	v_mov_b32_e32 v75, v67
	v_mov_b32_e32 v76, v68
	v_mov_b32_e32 v77, v69
	v_permlane16_swap_b32_e32 v62, v70
	v_permlane16_swap_b32_e32 v63, v71
	v_permlane16_swap_b32_e32 v64, v72
	v_permlane16_swap_b32_e32 v65, v73
	v_permlane16_swap_b32_e32 v66, v74
	v_permlane16_swap_b32_e32 v67, v75
	v_permlane16_swap_b32_e32 v68, v76
	v_permlane16_swap_b32_e32 v69, v77
	v_max_f32_e32 v62, v62, v70
	v_max_f32_e32 v63, v63, v71
	v_max_f32_e32 v64, v64, v72
	v_max_f32_e32 v65, v65, v73
	v_max_f32_e32 v66, v66, v74
	v_max_f32_e32 v67, v67, v75
	v_max_f32_e32 v68, v68, v76
	v_max_f32_e32 v69, v69, v77
	v_mov_b32_e32 v70, v62
	v_mov_b32_e32 v71, v63
	v_mov_b32_e32 v72, v64
	v_mov_b32_e32 v73, v65
	v_mov_b32_e32 v74, v66
	v_mov_b32_e32 v75, v67
	v_mov_b32_e32 v76, v68
	v_mov_b32_e32 v77, v69
	v_permlane32_swap_b32_e32 v62, v70
	v_permlane32_swap_b32_e32 v63, v71
; __device__ __forceinline__ float wave_max(float v) {
; #pragma unroll
;     for (int o = 8; o >= 1; o >>= 1) v = fmaxf(v, __shfl_xor(v, o));
;     return rows_max(v); }
; __device__ __forceinline__ void nsa_unit(LAS unsigned char* lds, const Ctx& P, int l, int b, int hkv, int tb) {
;     ...
;                 for (int r = 0; r < 5; ++r) { const float mx = wave_max(vv); const unsigned long long bal = __ballot(vv == mx);
;                     const int js = __builtin_ctzll(bal); mask |= 1ull << js; if (lane == js) vv = -__builtin_inff(); }
	v_permlane32_swap_b32_e32 v64, v72
	v_permlane32_swap_b32_e32 v65, v73
	v_permlane32_swap_b32_e32 v66, v74
	v_permlane32_swap_b32_e32 v67, v75
	v_permlane32_swap_b32_e32 v68, v76
	v_permlane32_swap_b32_e32 v69, v77
	v_max_f32_e32 v62, v62, v70
	v_max_f32_e32 v63, v63, v71
	v_max_f32_e32 v64, v64, v72
	v_max_f32_e32 v65, v65, v73
	v_max_f32_e32 v66, v66, v74
	v_max_f32_e32 v67, v67, v75
	v_max_f32_e32 v68, v68, v76
	v_max_f32_e32 v69, v69, v77
	v_cmp_eq_f32_e64 s[4:5], v18, v62
	v_cmp_eq_f32_e64 s[8:9], v19, v63
	s_ff1_i32_b64 s26, s[4:5]
	s_ff1_i32_b64 s27, s[8:9]
	s_lshl_b64 s[18:19], 1, s26
	s_lshl_b64 s[20:21], 1, s27
	s_or_b64 s[46:47], s[46:47], s[18:19]
	s_or_b64 s[56:57], s[56:57], s[20:21]
	v_cmp_ne_u32_e64 s[4:5], s26, v99
	v_cmp_ne_u32_e64 s[8:9], s27, v99
	s_nop 0
	v_cndmask_b32_e64 v18, v242, v18, s[4:5]
	v_cndmask_b32_e64 v19, v242, v19, s[8:9]
	v_cmp_eq_f32_e64 s[4:5], v20, v64
	v_cmp_eq_f32_e64 s[8:9], v21, v65
	s_ff1_i32_b64 s26, s[4:5]
	s_ff1_i32_b64 s27, s[8:9]
	s_lshl_b64 s[18:19], 1, s26
	s_lshl_b64 s[20:21], 1, s27
	s_or_b64 s[58:59], s[58:59], s[18:19]
	s_or_b64 s[76:77], s[76:77], s[20:21]
	v_cmp_ne_u32_e64 s[4:5], s26, v99
	v_cmp_ne_u32_e64 s[8:9], s27, v99
	s_nop 0
	v_cndmask_b32_e64 v20, v242, v20, s[4:5]
	v_cndmask_b32_e64 v21, v242, v21, s[8:9]
	v_cmp_eq_f32_e64 s[4:5], v22, v66
	v_cmp_eq_f32_e64 s[8:9], v23, v67
	s_ff1_i32_b64 s26, s[4:5]
	s_ff1_i32_b64 s27, s[8:9]
	s_lshl_b64 s[18:19], 1, s26
	s_lshl_b64 s[20:21], 1, s27
	s_or_b64 s[82:83], s[82:83], s[18:19]
	s_or_b64 s[86:87], s[86:87], s[20:21]
	v_cmp_ne_u32_e64 s[4:5], s26, v99
	v_cmp_ne_u32_e64 s[8:9], s27, v99
	s_nop 0
	v_cndmask_b32_e64 v22, v242, v22, s[4:5]
	v_cndmask_b32_e64 v23, v242, v23, s[8:9]
	v_cmp_eq_f32_e64 s[4:5], v24, v68
	v_cmp_eq_f32_e64 s[8:9], v25, v69
	s_ff1_i32_b64 s26, s[4:5]
	s_ff1_i32_b64 s27, s[8:9]
	s_lshl_b64 s[18:19], 1, s26
	s_lshl_b64 s[20:21], 1, s27
	s_or_b64 s[16:17], s[16:17], s[18:19]
	s_or_b64 s[28:29], s[28:29], s[20:21]
	v_cmp_ne_u32_e64 s[4:5], s26, v99
	v_cmp_ne_u32_e64 s[8:9], s27, v99
	s_nop 0
	v_cndmask_b32_e64 v24, v242, v24, s[4:5]
	v_cndmask_b32_e64 v25, v242, v25, s[8:9]
	v_max_f32_dpp v62, v18, v18 row_ror:8 row_mask:0xf bank_mask:0xf
	v_max_f32_dpp v63, v19, v19 row_ror:8 row_mask:0xf bank_mask:0xf
	v_max_f32_dpp v64, v20, v20 row_ror:8 row_mask:0xf bank_mask:0xf
	v_max_f32_dpp v65, v21, v21 row_ror:8 row_mask:0xf bank_mask:0xf
	v_max_f32_dpp v66, v22, v22 row_ror:8 row_mask:0xf bank_mask:0xf
	v_max_f32_dpp v67, v23, v23 row_ror:8 row_mask:0xf bank_mask:0xf
	v_max_f32_dpp v68, v24, v24 row_ror:8 row_mask:0xf bank_mask:0xf
	v_max_f32_dpp v69, v25, v25 row_ror:8 row_mask:0xf bank_mask:0xf
	v_max_f32_dpp v62, v62, v62 row_ror:4 row_mask:0xf bank_mask:0xf
	v_max_f32_dpp v63, v63, v63 row_ror:4 row_mask:0xf bank_mask:0xf
	v_max_f32_dpp v64, v64, v64 row_ror:4 row_mask:0xf bank_mask:0xf
	v_max_f32_dpp v65, v65, v65 row_ror:4 row_mask:0xf bank_mask:0xf
	v_max_f32_dpp v66, v66, v66 row_ror:4 row_mask:0xf bank_mask:0xf
	v_max_f32_dpp v67, v67, v67 row_ror:4 row_mask:0xf bank_mask:0xf
	v_max_f32_dpp v68, v68, v68 row_ror:4 row_mask:0xf bank_mask:0xf
	v_max_f32_dpp v69, v69, v69 row_ror:4 row_mask:0xf bank_mask:0xf
	v_max_f32_dpp v62, v62, v62 row_ror:2 row_mask:0xf bank_mask:0xf
	v_max_f32_dpp v63, v63, v63 row_ror:2 row_mask:0xf bank_mask:0xf
	v_max_f32_dpp v64, v64, v64 row_ror:2 row_mask:0xf bank_mask:0xf
	v_max_f32_dpp v65, v65, v65 row_ror:2 row_mask:0xf bank_mask:0xf
	v_max_f32_dpp v66, v66, v66 row_ror:2 row_mask:0xf bank_mask:0xf
	v_max_f32_dpp v67, v67, v67 row_ror:2 row_mask:0xf bank_mask:0xf
	v_max_f32_dpp v68, v68, v68 row_ror:2 row_mask:0xf bank_mask:0xf
	v_max_f32_dpp v69, v69, v69 row_ror:2 row_mask:0xf bank_mask:0xf
	v_max_f32_dpp v62, v62, v62 row_ror:1 row_mask:0xf bank_mask:0xf
	v_max_f32_dpp v63, v63, v63 row_ror:1 row_mask:0xf bank_mask:0xf
	v_max_f32_dpp v64, v64, v64 row_ror:1 row_mask:0xf bank_mask:0xf
	v_max_f32_dpp v65, v65, v65 row_ror:1 row_mask:0xf bank_mask:0xf
	v_max_f32_dpp v66, v66, v66 row_ror:1 row_mask:0xf bank_mask:0xf
	v_max_f32_dpp v67, v67, v67 row_ror:1 row_mask:0xf bank_mask:0xf
	v_max_f32_dpp v68, v68, v68 row_ror:1 row_mask:0xf bank_mask:0xf
	v_max_f32_dpp v69, v69, v69 row_ror:1 row_mask:0xf bank_mask:0xf
	v_mov_b32_e32 v70, v62
	v_mov_b32_e32 v71, v63
	v_mov_b32_e32 v72, v64
	v_mov_b32_e32 v73, v65
	v_mov_b32_e32 v74, v66
	v_mov_b32_e32 v75, v67
	v_mov_b32_e32 v76, v68
	v_mov_b32_e32 v77, v69
	v_permlane16_swap_b32_e32 v62, v70
	v_permlane16_swap_b32_e32 v63, v71
	v_permlane16_swap_b32_e32 v64, v72
	v_permlane16_swap_b32_e32 v65, v73
	v_permlane16_swap_b32_e32 v66, v74
	v_permlane16_swap_b32_e32 v67, v75
	v_permlane16_swap_b32_e32 v68, v76
	v_permlane16_swap_b32_e32 v69, v77
	v_max_f32_e32 v62, v62, v70
	v_max_f32_e32 v63, v63, v71
	v_max_f32_e32 v64, v64, v72
	v_max_f32_e32 v65, v65, v73
	v_max_f32_e32 v66, v66, v74
	v_max_f32_e32 v67, v67, v75
	v_max_f32_e32 v68, v68, v76
	v_max_f32_e32 v69, v69, v77
	v_mov_b32_e32 v70, v62
	v_mov_b32_e32 v71, v63
	v_mov_b32_e32 v72, v64
	v_mov_b32_e32 v73, v65
	v_mov_b32_e32 v74, v66
	v_mov_b32_e32 v75, v67
	v_mov_b32_e32 v76, v68
	v_mov_b32_e32 v77, v69
	v_permlane32_swap_b32_e32 v62, v70
	v_permlane32_swap_b32_e32 v63, v71
	v_permlane32_swap_b32_e32 v64, v72
	v_permlane32_swap_b32_e32 v65, v73
	v_permlane32_swap_b32_e32 v66, v74
	v_permlane32_swap_b32_e32 v67, v75
	v_permlane32_swap_b32_e32 v68, v76
	v_permlane32_swap_b32_e32 v69, v77
	v_max_f32_e32 v62, v62, v70
	v_max_f32_e32 v63, v63, v71
	v_max_f32_e32 v64, v64, v72
	v_max_f32_e32 v65, v65, v73
	v_max_f32_e32 v66, v66, v74
	v_max_f32_e32 v67, v67, v75
	v_max_f32_e32 v68, v68, v76
	v_max_f32_e32 v69, v69, v77
	v_cmp_eq_f32_e64 s[4:5], v18, v62
	v_cmp_eq_f32_e64 s[8:9], v19, v63
	s_ff1_i32_b64 s26, s[4:5]
	s_ff1_i32_b64 s27, s[8:9]
	s_lshl_b64 s[18:19], 1, s26
	s_lshl_b64 s[20:21], 1, s27
	s_or_b64 s[46:47], s[46:47], s[18:19]
	s_or_b64 s[56:57], s[56:57], s[20:21]
	v_cmp_eq_f32_e64 s[4:5], v20, v64
	v_cmp_eq_f32_e64 s[8:9], v21, v65
	s_ff1_i32_b64 s26, s[4:5]
	s_ff1_i32_b64 s27, s[8:9]
	s_lshl_b64 s[18:19], 1, s26
	s_lshl_b64 s[20:21], 1, s27
	s_or_b64 s[58:59], s[58:59], s[18:19]
	s_or_b64 s[76:77], s[76:77], s[20:21]
	v_cmp_eq_f32_e64 s[4:5], v22, v66
	v_cmp_eq_f32_e64 s[8:9], v23, v67
	s_ff1_i32_b64 s26, s[4:5]
	s_ff1_i32_b64 s27, s[8:9]
	s_lshl_b64 s[18:19], 1, s26
	s_lshl_b64 s[20:21], 1, s27
	s_or_b64 s[82:83], s[82:83], s[18:19]
	s_or_b64 s[86:87], s[86:87], s[20:21]
	v_cmp_eq_f32_e64 s[4:5], v24, v68
	v_cmp_eq_f32_e64 s[8:9], v25, v69
	s_ff1_i32_b64 s26, s[4:5]
	s_ff1_i32_b64 s27, s[8:9]
	s_lshl_b64 s[18:19], 1, s26
	s_lshl_b64 s[20:21], 1, s27
	s_or_b64 s[16:17], s[16:17], s[18:19]
	s_or_b64 s[28:29], s[28:29], s[20:21]
; __device__ __forceinline__ void nsa_unit(LAS unsigned char* lds, const Ctx& P, int l, int b, int hkv, int tb) {
;     ...
;         for (int tt = 0; tt < 8; ++tt) { const int tl = 8 * wid + tt;
;             unsigned long long mask;
;             if (qb <= 7) mask = (2ull << qb) - 1ull;
;             else {
;                 const float v = impb[(0 * 64 + tl) * 64 + lane] + impb[(1 * 64 + tl) * 64 + lane] + impb[(2 * 64 + tl) * 64 + lane] + impb[(3 * 64 + tl) * 64 + lane];
;                 float vv = (lane >= 1 && lane <= qb - 2) ? v : -__builtin_inff();
;                 mask = 1ull | (1ull << qb) | (1ull << (qb - 1));
; #pragma unroll
;                 for (int r = 0; r < 5; ++r) { const float mx = wave_max(vv); const unsigned long long bal = __ballot(vv == mx);
;                     const int js = __builtin_ctzll(bal); mask |= 1ull << js; if (lane == js) vv = -__builtin_inff(); }
;             }
;             if (lane == 0) sels[tl] = mask; }
.Ltk_write:
	v_lshlrev_b32_e32 v26, 6, v155
	v_add_u32_e32 v26, 0x1d000, v26
	s_and_saveexec_b64 s[0:1], s[12:13]
	v_mov_b32_e32 v28, s46
	v_mov_b32_e32 v29, s47
	ds_write_b64 v26, v[28:29]
	v_mov_b32_e32 v30, s56
	v_mov_b32_e32 v31, s57
	ds_write_b64 v26, v[30:31] offset:8
	v_mov_b32_e32 v28, s58
	v_mov_b32_e32 v29, s59
	ds_write_b64 v26, v[28:29] offset:16
	v_mov_b32_e32 v30, s76
	v_mov_b32_e32 v31, s77
	ds_write_b64 v26, v[30:31] offset:24
	v_mov_b32_e32 v28, s82
	v_mov_b32_e32 v29, s83
	ds_write_b64 v26, v[28:29] offset:32
	v_mov_b32_e32 v30, s86
	v_mov_b32_e32 v31, s87
	ds_write_b64 v26, v[30:31] offset:40
	v_mov_b32_e32 v28, s16
	v_mov_b32_e32 v29, s17
	ds_write_b64 v26, v[28:29] offset:48
	v_mov_b32_e32 v30, s28
	v_mov_b32_e32 v31, s29
	ds_write_b64 v26, v[30:31] offset:56

; __device__ __forceinline__ float bf2f(bf16_t v) { return __uint_as_float(((unsigned)v) << 16); }
; __device__ __forceinline__ float sigmoidf_(float x) { return __builtin_amdgcn_rcpf(1.0f + __expf(-x)); }
; __device__ __forceinline__ void nsa_unit(LAS unsigned char* lds, const Ctx& P, int l, int b, int hkv, int tb) {
;     ...
;         f32x4 o[2][4]; float m[2], lsum[2];
; #pragma unroll
;         for (int sb = 0; sb < 2; ++sb) { m[sb] = NEGBIG; lsum[sb] = 0.f;
; #pragma unroll
;             for (int dt = 0; dt < 4; ++dt) o[sb][dt] = (f32x4){0.f, 0.f, 0.f, 0.f}; }
;     ...
; #pragma unroll
;         for (int sb = 0; sb < 2; ++sb) { const float g1 = sigmoidf_(bf2f(H[tok[sb] * LDH + C_GL + 16 + hq]) + P.in[21][l * 48 + 16 + hq]) / fmaxf(lsum[sb], 1e-30f);
.LBB0_588:
	v_max_f32_e32 v18, v106, v106
	v_max_f32_e32 v19, 0xda24260, v18
	v_max_f32_e32 v18, v105, v105
	v_max_f32_e32 v18, 0xda24260, v18
	s_branch .LBB0_597
.LBB0_596:
	v_mov_b32_e32 v38, v1
	v_mov_b32_e32 v39, v1
	v_mov_b32_e32 v40, v1
	v_mov_b32_e32 v41, v1
	v_mov_b64_e32 v[44:45], v[40:41]
	v_mov_b64_e32 v[48:49], v[40:41]
	v_mov_b64_e32 v[52:53], v[40:41]
	v_mov_b64_e32 v[22:23], v[38:39]
	v_mov_b64_e32 v[26:27], v[38:39]
	v_mov_b64_e32 v[34:35], v[38:39]
	v_mov_b64_e32 v[30:31], v[38:39]
	v_mov_b32_e32 v19, 0xda24260
	v_mov_b32_e32 v18, 0xda24260
	v_mov_b64_e32 v[42:43], v[38:39]
	v_mov_b64_e32 v[46:47], v[38:39]
	v_mov_b64_e32 v[50:51], v[38:39]
	v_mov_b64_e32 v[24:25], v[40:41]
	v_mov_b64_e32 v[28:29], v[40:41]
	v_mov_b64_e32 v[36:37], v[40:41]
	v_mov_b64_e32 v[32:33], v[40:41]

; __device__ __forceinline__ void tconv_tile(LAS float* tile, const float* src, int ld, int k0, int n0, int mode, bf16_t* dst, int K) {
;     ...
;     for (int it = 0; it < 2; ++it) { const int idx = tid + it * 512, kk = idx >> 4, n4 = (idx & 15) * 4, nn = n0 + n4; int oc = nn; bool valid = true;
;         if (mode == 1) { if (nn < 7680) oc = nn; else if (nn < 18944) oc = nn + 48; else if (nn < INW) oc = 7680 + (nn - 18944); else valid = false; }
;         f32x4 v = (f32x4){0.f, 0.f, 0.f, 0.f}; if (valid) v = *(const f32x4*)(src + (size_t)(k0 + kk) * ld + oc);
; __device__ __forceinline__ void prologue(LAS unsigned char* lds, const Ctx& P, int l) {
;     ...
;     for (int t = blockIdx.x; t < T_ALL; t += G) {
;         int q = t;
;         if (q < T_IN) { const int kt = q & 31, ntl = q >> 5; tconv_tile(tile, P.in[3] + (size_t)l * DM * INW, INW, kt * 64, ntl * 64, 1, (bf16_t*)(ws + WS_WIN), DM); continue; }
.Ltc1_d40:
	v_mov_b32_e32 v58, 0
	v_mov_b32_e32 v59, 0
	v_mov_b32_e32 v60, 0
	v_mov_b32_e32 v61, 0
	v_mov_b32_e32 v62, 0
	v_mov_b32_e32 v63, 0
	v_mov_b32_e32 v64, 0
	v_mov_b32_e32 v65, 0
	v_mul_u32_u24_e32 v26, s28, v20
	v_add_lshl_u32 v26, v26, v21, 2
	s_lshl_b32 s0, s28, 7
	v_add_u32_e32 v27, s0, v26
	v_cmp_gt_i32_e32 vcc, s29, v21
	s_and_saveexec_b64 s[0:1], vcc
	global_load_dwordx4 v[58:61], v26, s[26:27]
	global_load_dwordx4 v[62:65], v27, s[26:27]
	s_mov_b64 exec, s[0:1]
	s_add_u32 s24, s24, s34
	s_min_u32 s0, s24, 14015
	s_mov_b32 s21, s0
	s_mov_b32 s0, s21
	s_cmpk_lt_u32 s0, 9600
	s_cbranch_scc0 .Ltc1_c54
	s_and_b32 s1, s0, 31
	s_lshl_b32 s1, s1, 6
	s_lshr_b32 s21, s0, 5
	s_lshl_b32 s21, s21, 6
	s_movk_i32 s29, 64
	s_cmpk_lt_u32 s21, 7680
	s_cbranch_scc1 .Ltc1_n56
	s_cmpk_lt_u32 s21, 18944
	s_cbranch_scc0 .Ltc1_t55
	s_add_u32 s21, s21, 48
	s_branch .Ltc1_n56

; __device__ __forceinline__ void tconv_tile(LAS float* tile, const float* src, int ld, int k0, int n0, int mode, bf16_t* dst, int K) {
;     ...
;     for (int it = 0; it < 2; ++it) { const int idx = tid + it * 512, kk = idx >> 4, n4 = (idx & 15) * 4, nn = n0 + n4; int oc = nn; bool valid = true;
;         if (mode == 1) { if (nn < 7680) oc = nn; else if (nn < 18944) oc = nn + 48; else if (nn < INW) oc = 7680 + (nn - 18944); else valid = false; }
;         f32x4 v = (f32x4){0.f, 0.f, 0.f, 0.f}; if (valid) v = *(const f32x4*)(src + (size_t)(k0 + kk) * ld + oc);
; __device__ __forceinline__ void prologue(LAS unsigned char* lds, const Ctx& P, int l) {
;     ...
;     for (int t = blockIdx.x; t < T_ALL; t += G) {
;         int q = t;
;         if (q < T_IN) { const int kt = q & 31, ntl = q >> 5; tconv_tile(tile, P.in[3] + (size_t)l * DM * INW, INW, kt * 64, ntl * 64, 1, (bf16_t*)(ws + WS_WIN), DM); continue; }
.Ltc1_d53:
	v_mov_b32_e32 v78, 0
	v_mov_b32_e32 v79, 0
	v_mov_b32_e32 v80, 0
	v_mov_b32_e32 v81, 0
	v_mov_b32_e32 v82, 0
	v_mov_b32_e32 v83, 0
	v_mov_b32_e32 v84, 0
	v_mov_b32_e32 v85, 0
	v_mul_u32_u24_e32 v26, s28, v20
	v_add_lshl_u32 v26, v26, v21, 2
	s_lshl_b32 s0, s28, 7
	v_add_u32_e32 v27, s0, v26
	v_cmp_gt_i32_e32 vcc, s29, v21
	s_and_saveexec_b64 s[0:1], vcc
	global_load_dwordx4 v[78:81], v26, s[26:27]
	global_load_dwordx4 v[82:85], v27, s[26:27]
	s_mov_b64 exec, s[0:1]
	s_add_u32 s24, s24, s34
	s_min_u32 s0, s24, 14015
	s_mov_b32 s21, s0
	s_mov_b32 s0, s21
	s_cmpk_lt_u32 s0, 9600
	s_cbranch_scc0 .Ltc1_c67
	s_and_b32 s1, s0, 31
	s_lshl_b32 s1, s1, 6
	s_lshr_b32 s21, s0, 5
	s_lshl_b32 s21, s21, 6
	s_movk_i32 s29, 64
	s_cmpk_lt_u32 s21, 7680
	s_cbranch_scc1 .Ltc1_n69
	s_cmpk_lt_u32 s21, 18944
	s_cbranch_scc0 .Ltc1_t68
	s_add_u32 s21, s21, 48
	s_branch .Ltc1_n69

; __device__ __forceinline__ unsigned cvt_pk_bf16(float lo, float hi) { unsigned r; asm("v_cvt_pk_bf16_f32 %0, %1, %2" : "=v"(r) : "v"(lo), "v"(hi)); return r; }
; __device__ __forceinline__ void tconv_tile(LAS float* tile, const float* src, int ld, int k0, int n0, int mode, bf16_t* dst, int K) {
;     ...
;     for (int it = 0; it < 2; ++it) { const int idx = tid + it * 512, kk = idx >> 4, n4 = (idx & 15) * 4, nn = n0 + n4; int oc = nn; bool valid = true;
;         if (mode == 1) { if (nn < 7680) oc = nn; else if (nn < 18944) oc = nn + 48; else if (nn < INW) oc = 7680 + (nn - 18944); else valid = false; }
;         f32x4 v = (f32x4){0.f, 0.f, 0.f, 0.f}; if (valid) v = *(const f32x4*)(src + (size_t)(k0 + kk) * ld + oc);
;         tile[kk * 65 + n4 + 0] = v[0]; tile[kk * 65 + n4 + 1] = v[1]; tile[kk * 65 + n4 + 2] = v[2]; tile[kk * 65 + n4 + 3] = v[3]; }
;     __syncthreads();
;     { const int n = tid >> 3, k8 = (tid & 7) * 8; float v[8];
; #pragma unroll
;         for (int e = 0; e < 8; ++e) v[e] = tile[(k8 + e) * 65 + n];
;         u32x4 w; w.x = cvt_pk_bf16(v[0], v[1]); w.y = cvt_pk_bf16(v[2], v[3]); w.z = cvt_pk_bf16(v[4], v[5]); w.w = cvt_pk_bf16(v[6], v[7]);
;         *(u32x4*)(dst + (size_t)(n0 + n) * K + k0 + k8) = w; }
; __device__ __forceinline__ void prologue(LAS unsigned char* lds, const Ctx& P, int l) {
;     ...
;     for (int t = blockIdx.x; t < T_ALL; t += G) {
;         int q = t;
;         if (q < T_IN) { const int kt = q & 31, ntl = q >> 5; tconv_tile(tile, P.in[3] + (size_t)l * DM * INW, INW, kt * 64, ntl * 64, 1, (bf16_t*)(ws + WS_WIN), DM); continue; }
.Ltc1_d66:
	v_mov_b32_e32 v86, 0
	v_mov_b32_e32 v87, 0
	v_mov_b32_e32 v88, 0
	v_mov_b32_e32 v89, 0
	v_mov_b32_e32 v90, 0
	v_mov_b32_e32 v91, 0
	v_mov_b32_e32 v92, 0
	v_mov_b32_e32 v93, 0
	v_mul_u32_u24_e32 v26, s28, v20
	v_add_lshl_u32 v26, v26, v21, 2
	s_lshl_b32 s0, s28, 7
	v_add_u32_e32 v27, s0, v26
	v_cmp_gt_i32_e32 vcc, s29, v21
	s_and_saveexec_b64 s[0:1], vcc
	global_load_dwordx4 v[86:89], v26, s[26:27]
	global_load_dwordx4 v[90:93], v27, s[26:27]
	s_mov_b64 exec, s[0:1]
	s_add_u32 s24, s24, s34
	s_cmpk_ge_u32 s25, 14016
	s_cbranch_scc1 .Ltc1_exit
	s_waitcnt vmcnt(10)
	v_add_u32_e32 v28, 0, v22
	ds_write2_b32 v28, v34, v35 offset1:1
	ds_write2_b32 v28, v36, v37 offset0:2 offset1:3
	v_add_u32_e32 v28, 0x2080, v28
	ds_write2_b32 v28, v38, v39 offset1:1
	ds_write2_b32 v28, v40, v41 offset0:2 offset1:3
	s_mov_b32 s21, s25
	s_mov_b32 s0, s21
	s_cmpk_lt_u32 s0, 9600
	s_cbranch_scc0 .Ltc1_c80
	s_and_b32 s1, s0, 31
	s_lshl_b32 s1, s1, 6
	s_lshr_b32 s21, s0, 5
	s_lshl_b32 s21, s21, 17
	s_add_u32 s1, s1, s21
	s_lshl_b32 s1, s1, 1
	s_add_u32 s1, s1, 0x4001000
	s_add_u32 s30, s68, s1
	s_addc_u32 s31, s69, 0
	s_movk_i32 s20, 0x800
	s_branch .Ltc1_d79

; __device__ __forceinline__ unsigned cvt_pk_bf16(float lo, float hi) { unsigned r; asm("v_cvt_pk_bf16_f32 %0, %1, %2" : "=v"(r) : "v"(lo), "v"(hi)); return r; }
; __device__ __forceinline__ void tconv_tile(LAS float* tile, const float* src, int ld, int k0, int n0, int mode, bf16_t* dst, int K) {
;     ...
;     for (int it = 0; it < 2; ++it) { const int idx = tid + it * 512, kk = idx >> 4, n4 = (idx & 15) * 4, nn = n0 + n4; int oc = nn; bool valid = true;
;         if (mode == 1) { if (nn < 7680) oc = nn; else if (nn < 18944) oc = nn + 48; else if (nn < INW) oc = 7680 + (nn - 18944); else valid = false; }
;         f32x4 v = (f32x4){0.f, 0.f, 0.f, 0.f}; if (valid) v = *(const f32x4*)(src + (size_t)(k0 + kk) * ld + oc);
;         tile[kk * 65 + n4 + 0] = v[0]; tile[kk * 65 + n4 + 1] = v[1]; tile[kk * 65 + n4 + 2] = v[2]; tile[kk * 65 + n4 + 3] = v[3]; }
;     __syncthreads();
;     { const int n = tid >> 3, k8 = (tid & 7) * 8; float v[8];
; #pragma unroll
;         for (int e = 0; e < 8; ++e) v[e] = tile[(k8 + e) * 65 + n];
;         u32x4 w; w.x = cvt_pk_bf16(v[0], v[1]); w.y = cvt_pk_bf16(v[2], v[3]); w.z = cvt_pk_bf16(v[4], v[5]); w.w = cvt_pk_bf16(v[6], v[7]);
;         *(u32x4*)(dst + (size_t)(n0 + n) * K + k0 + k8) = w; }
; __device__ __forceinline__ void prologue(LAS unsigned char* lds, const Ctx& P, int l) {
;     ...
;     for (int t = blockIdx.x; t < T_ALL; t += G) {
;         int q = t;
;         if (q < T_IN) { const int kt = q & 31, ntl = q >> 5; tconv_tile(tile, P.in[3] + (size_t)l * DM * INW, INW, kt * 64, ntl * 64, 1, (bf16_t*)(ws + WS_WIN), DM); continue; }
.Ltc1_d86:
	v_mov_b32_e32 v34, 0
	v_mov_b32_e32 v35, 0
	v_mov_b32_e32 v36, 0
	v_mov_b32_e32 v37, 0
	v_mov_b32_e32 v38, 0
	v_mov_b32_e32 v39, 0
	v_mov_b32_e32 v40, 0
	v_mov_b32_e32 v41, 0
	v_mul_u32_u24_e32 v26, s28, v20
	v_add_lshl_u32 v26, v26, v21, 2
	s_lshl_b32 s0, s28, 7
	v_add_u32_e32 v27, s0, v26
	v_cmp_gt_i32_e32 vcc, s29, v21
	s_and_saveexec_b64 s[0:1], vcc
	global_load_dwordx4 v[34:37], v26, s[26:27]
	global_load_dwordx4 v[38:41], v27, s[26:27]
	s_mov_b64 exec, s[0:1]
	s_add_u32 s24, s24, s34
	s_cmpk_ge_u32 s25, 14016
	s_cbranch_scc1 .Ltc1_exit
	s_waitcnt vmcnt(11)
	v_add_u32_e32 v28, 16896, v22
	ds_write2_b32 v28, v42, v43 offset1:1
	ds_write2_b32 v28, v44, v45 offset0:2 offset1:3
	v_add_u32_e32 v28, 0x2080, v28
	ds_write2_b32 v28, v46, v47 offset1:1
	ds_write2_b32 v28, v48, v49 offset0:2 offset1:3
	s_mov_b32 s21, s25
	s_mov_b32 s0, s21
	s_cmpk_lt_u32 s0, 9600
	s_cbranch_scc0 .Ltc1_c100
	s_and_b32 s1, s0, 31
	s_lshl_b32 s1, s1, 6
	s_lshr_b32 s21, s0, 5
	s_lshl_b32 s21, s21, 17
	s_add_u32 s1, s1, s21
	s_lshl_b32 s1, s1, 1
	s_add_u32 s1, s1, 0x4001000
	s_add_u32 s30, s68, s1
	s_addc_u32 s31, s69, 0
	s_movk_i32 s20, 0x800
	s_branch .Ltc1_d99

; __device__ __forceinline__ unsigned cvt_pk_bf16(float lo, float hi) { unsigned r; asm("v_cvt_pk_bf16_f32 %0, %1, %2" : "=v"(r) : "v"(lo), "v"(hi)); return r; }
; __device__ __forceinline__ void tconv_tile(LAS float* tile, const float* src, int ld, int k0, int n0, int mode, bf16_t* dst, int K) {
;     ...
;     for (int it = 0; it < 2; ++it) { const int idx = tid + it * 512, kk = idx >> 4, n4 = (idx & 15) * 4, nn = n0 + n4; int oc = nn; bool valid = true;
;         if (mode == 1) { if (nn < 7680) oc = nn; else if (nn < 18944) oc = nn + 48; else if (nn < INW) oc = 7680 + (nn - 18944); else valid = false; }
;         f32x4 v = (f32x4){0.f, 0.f, 0.f, 0.f}; if (valid) v = *(const f32x4*)(src + (size_t)(k0 + kk) * ld + oc);
;         tile[kk * 65 + n4 + 0] = v[0]; tile[kk * 65 + n4 + 1] = v[1]; tile[kk * 65 + n4 + 2] = v[2]; tile[kk * 65 + n4 + 3] = v[3]; }
;     __syncthreads();
;     { const int n = tid >> 3, k8 = (tid & 7) * 8; float v[8];
; #pragma unroll
;         for (int e = 0; e < 8; ++e) v[e] = tile[(k8 + e) * 65 + n];
;         u32x4 w; w.x = cvt_pk_bf16(v[0], v[1]); w.y = cvt_pk_bf16(v[2], v[3]); w.z = cvt_pk_bf16(v[4], v[5]); w.w = cvt_pk_bf16(v[6], v[7]);
;         *(u32x4*)(dst + (size_t)(n0 + n) * K + k0 + k8) = w; }
; __device__ __forceinline__ void prologue(LAS unsigned char* lds, const Ctx& P, int l) {
;     ...
;     for (int t = blockIdx.x; t < T_ALL; t += G) {
;         int q = t;
;         if (q < T_IN) { const int kt = q & 31, ntl = q >> 5; tconv_tile(tile, P.in[3] + (size_t)l * DM * INW, INW, kt * 64, ntl * 64, 1, (bf16_t*)(ws + WS_WIN), DM); continue; }
.Ltc1_d106:
	v_mov_b32_e32 v42, 0
	v_mov_b32_e32 v43, 0
	v_mov_b32_e32 v44, 0
	v_mov_b32_e32 v45, 0
	v_mov_b32_e32 v46, 0
	v_mov_b32_e32 v47, 0
	v_mov_b32_e32 v48, 0
	v_mov_b32_e32 v49, 0
	v_mul_u32_u24_e32 v26, s28, v20
	v_add_lshl_u32 v26, v26, v21, 2
	s_lshl_b32 s0, s28, 7
	v_add_u32_e32 v27, s0, v26
	v_cmp_gt_i32_e32 vcc, s29, v21
	s_and_saveexec_b64 s[0:1], vcc
	global_load_dwordx4 v[42:45], v26, s[26:27]
	global_load_dwordx4 v[46:49], v27, s[26:27]
	s_mov_b64 exec, s[0:1]
	s_add_u32 s24, s24, s34
	s_cmpk_ge_u32 s25, 14016
	s_cbranch_scc1 .Ltc1_exit
	s_waitcnt vmcnt(12)
	v_add_u32_e32 v28, 0, v22
	ds_write2_b32 v28, v50, v51 offset1:1
	ds_write2_b32 v28, v52, v53 offset0:2 offset1:3
	v_add_u32_e32 v28, 0x2080, v28
	ds_write2_b32 v28, v54, v55 offset1:1
	ds_write2_b32 v28, v56, v57 offset0:2 offset1:3
	s_mov_b32 s21, s25
	s_mov_b32 s0, s21
	s_cmpk_lt_u32 s0, 9600
	s_cbranch_scc0 .Ltc1_c120
	s_and_b32 s1, s0, 31
	s_lshl_b32 s1, s1, 6
	s_lshr_b32 s21, s0, 5
	s_lshl_b32 s21, s21, 17
	s_add_u32 s1, s1, s21
	s_lshl_b32 s1, s1, 1
	s_add_u32 s1, s1, 0x4001000
	s_add_u32 s30, s68, s1
	s_addc_u32 s31, s69, 0
	s_movk_i32 s20, 0x800
	s_branch .Ltc1_d119

; #define LAS __attribute__((address_space(3)))
; __device__ __forceinline__ unsigned cvt_pk_bf16(float lo, float hi) { unsigned r; asm("v_cvt_pk_bf16_f32 %0, %1, %2" : "=v"(r) : "v"(lo), "v"(hi)); return r; }
; __device__ __forceinline__ int opaque_tid() { int t = threadIdx.x; asm volatile("" : "+v"(t)); return t; }
; __device__ __forceinline__ void tconv_tile(LAS float* tile, const float* src, int ld, int k0, int n0, int mode, bf16_t* dst, int K) {
;     const int tid = opaque_tid();
; #pragma unroll
;     for (int it = 0; it < 2; ++it) { const int idx = tid + it * 512, kk = idx >> 4, n4 = (idx & 15) * 4, nn = n0 + n4; int oc = nn; bool valid = true;
;         if (mode == 1) { if (nn < 7680) oc = nn; else if (nn < 18944) oc = nn + 48; else if (nn < INW) oc = 7680 + (nn - 18944); else valid = false; }
;         f32x4 v = (f32x4){0.f, 0.f, 0.f, 0.f}; if (valid) v = *(const f32x4*)(src + (size_t)(k0 + kk) * ld + oc);
;         tile[kk * 65 + n4 + 0] = v[0]; tile[kk * 65 + n4 + 1] = v[1]; tile[kk * 65 + n4 + 2] = v[2]; tile[kk * 65 + n4 + 3] = v[3]; }
;     __syncthreads();
;     { const int n = tid >> 3, k8 = (tid & 7) * 8; float v[8];
; #pragma unroll
;         for (int e = 0; e < 8; ++e) v[e] = tile[(k8 + e) * 65 + n];
;         u32x4 w; w.x = cvt_pk_bf16(v[0], v[1]); w.y = cvt_pk_bf16(v[2], v[3]); w.z = cvt_pk_bf16(v[4], v[5]); w.w = cvt_pk_bf16(v[6], v[7]);
;         *(u32x4*)(dst + (size_t)(n0 + n) * K + k0 + k8) = w; }
;     __syncthreads();
; }
; __device__ __forceinline__ void prologue(LAS unsigned char* lds, const Ctx& P, int l) {
;     unsigned char* ws = P.ws; LAS float* tile = (LAS float*)lds;
;     const int tid = opaque_tid(), G = gridDim.x;
;     const int T_IN = 32 * 300, T_BR = 4 * 512, T_OUT = 1024, T_MEM = 1024, T_W1 = 256, T_WA = 64;
;     const int T_ALL = T_IN + T_BR + T_OUT + T_MEM + T_W1 + T_WA;
;     for (int t = blockIdx.x; t < T_ALL; t += G) {
;         int q = t;
;         if (q < T_IN) { const int kt = q & 31, ntl = q >> 5; tconv_tile(tile, P.in[3] + (size_t)l * DM * INW, INW, kt * 64, ntl * 64, 1, (bf16_t*)(ws + WS_WIN), DM); continue; }
.Ltc1_d126:
	v_mov_b32_e32 v50, 0
	v_mov_b32_e32 v51, 0
	v_mov_b32_e32 v52, 0
	v_mov_b32_e32 v53, 0
	v_mov_b32_e32 v54, 0
	v_mov_b32_e32 v55, 0
	v_mov_b32_e32 v56, 0
	v_mov_b32_e32 v57, 0
	v_mul_u32_u24_e32 v26, s28, v20
	v_add_lshl_u32 v26, v26, v21, 2
	s_lshl_b32 s0, s28, 7
	v_add_u32_e32 v27, s0, v26
	v_cmp_gt_i32_e32 vcc, s29, v21
	s_and_saveexec_b64 s[0:1], vcc
	global_load_dwordx4 v[50:53], v26, s[26:27]
	global_load_dwordx4 v[54:57], v27, s[26:27]
	s_mov_b64 exec, s[0:1]
	s_add_u32 s24, s24, s34
	s_cmpk_ge_u32 s25, 14016
	s_cbranch_scc1 .Ltc1_exit
	s_waitcnt vmcnt(13)
	v_add_u32_e32 v28, 16896, v22
	ds_write2_b32 v28, v58, v59 offset1:1
	ds_write2_b32 v28, v60, v61 offset0:2 offset1:3
	v_add_u32_e32 v28, 0x2080, v28
	ds_write2_b32 v28, v62, v63 offset1:1
	ds_write2_b32 v28, v64, v65 offset0:2 offset1:3
	s_mov_b32 s21, s25
	s_mov_b32 s0, s21
	s_cmpk_lt_u32 s0, 9600
	s_cbranch_scc0 .Ltc1_c140
	s_and_b32 s1, s0, 31
	s_lshl_b32 s1, s1, 6
	s_lshr_b32 s21, s0, 5
	s_lshl_b32 s21, s21, 17
	s_add_u32 s1, s1, s21
	s_lshl_b32 s1, s1, 1
	s_add_u32 s1, s1, 0x4001000
	s_add_u32 s30, s68, s1
	s_addc_u32 s31, s69, 0
	s_movk_i32 s20, 0x800
	s_branch .Ltc1_d139

; #define LAS __attribute__((address_space(3)))
; __device__ __forceinline__ unsigned cvt_pk_bf16(float lo, float hi) { unsigned r; asm("v_cvt_pk_bf16_f32 %0, %1, %2" : "=v"(r) : "v"(lo), "v"(hi)); return r; }
; __device__ __forceinline__ int opaque_tid() { int t = threadIdx.x; asm volatile("" : "+v"(t)); return t; }
; __device__ __forceinline__ void tconv_tile(LAS float* tile, const float* src, int ld, int k0, int n0, int mode, bf16_t* dst, int K) {
;     const int tid = opaque_tid();
; #pragma unroll
;     for (int it = 0; it < 2; ++it) { const int idx = tid + it * 512, kk = idx >> 4, n4 = (idx & 15) * 4, nn = n0 + n4; int oc = nn; bool valid = true;
;         if (mode == 1) { if (nn < 7680) oc = nn; else if (nn < 18944) oc = nn + 48; else if (nn < INW) oc = 7680 + (nn - 18944); else valid = false; }
;         f32x4 v = (f32x4){0.f, 0.f, 0.f, 0.f}; if (valid) v = *(const f32x4*)(src + (size_t)(k0 + kk) * ld + oc);
;         tile[kk * 65 + n4 + 0] = v[0]; tile[kk * 65 + n4 + 1] = v[1]; tile[kk * 65 + n4 + 2] = v[2]; tile[kk * 65 + n4 + 3] = v[3]; }
;     __syncthreads();
;     { const int n = tid >> 3, k8 = (tid & 7) * 8; float v[8];
; #pragma unroll
;         for (int e = 0; e < 8; ++e) v[e] = tile[(k8 + e) * 65 + n];
;         u32x4 w; w.x = cvt_pk_bf16(v[0], v[1]); w.y = cvt_pk_bf16(v[2], v[3]); w.z = cvt_pk_bf16(v[4], v[5]); w.w = cvt_pk_bf16(v[6], v[7]);
;         *(u32x4*)(dst + (size_t)(n0 + n) * K + k0 + k8) = w; }
;     __syncthreads();
; }
; __device__ __forceinline__ void prologue(LAS unsigned char* lds, const Ctx& P, int l) {
;     unsigned char* ws = P.ws; LAS float* tile = (LAS float*)lds;
;     const int tid = opaque_tid(), G = gridDim.x;
;     const int T_IN = 32 * 300, T_BR = 4 * 512, T_OUT = 1024, T_MEM = 1024, T_W1 = 256, T_WA = 64;
;     const int T_ALL = T_IN + T_BR + T_OUT + T_MEM + T_W1 + T_WA;
;     for (int t = blockIdx.x; t < T_ALL; t += G) {
;         int q = t;
;         if (q < T_IN) { const int kt = q & 31, ntl = q >> 5; tconv_tile(tile, P.in[3] + (size_t)l * DM * INW, INW, kt * 64, ntl * 64, 1, (bf16_t*)(ws + WS_WIN), DM); continue; }
.Ltc1_d146:
	v_mov_b32_e32 v58, 0
	v_mov_b32_e32 v59, 0
	v_mov_b32_e32 v60, 0
	v_mov_b32_e32 v61, 0
	v_mov_b32_e32 v62, 0
	v_mov_b32_e32 v63, 0
	v_mov_b32_e32 v64, 0
	v_mov_b32_e32 v65, 0
	v_mul_u32_u24_e32 v26, s28, v20
	v_add_lshl_u32 v26, v26, v21, 2
	s_lshl_b32 s0, s28, 7
	v_add_u32_e32 v27, s0, v26
	v_cmp_gt_i32_e32 vcc, s29, v21
	s_and_saveexec_b64 s[0:1], vcc
	global_load_dwordx4 v[58:61], v26, s[26:27]
	global_load_dwordx4 v[62:65], v27, s[26:27]
	s_mov_b64 exec, s[0:1]
	s_add_u32 s24, s24, s34
	s_cmpk_ge_u32 s25, 14016
	s_cbranch_scc1 .Ltc1_exit
	s_waitcnt vmcnt(14)
	v_add_u32_e32 v28, 0, v22
	ds_write2_b32 v28, v78, v79 offset1:1
	ds_write2_b32 v28, v80, v81 offset0:2 offset1:3
	v_add_u32_e32 v28, 0x2080, v28
	ds_write2_b32 v28, v82, v83 offset1:1
	ds_write2_b32 v28, v84, v85 offset0:2 offset1:3
	s_mov_b32 s21, s25
	s_mov_b32 s0, s21
	s_cmpk_lt_u32 s0, 9600
	s_cbranch_scc0 .Ltc1_c160
	s_and_b32 s1, s0, 31
	s_lshl_b32 s1, s1, 6
	s_lshr_b32 s21, s0, 5
	s_lshl_b32 s21, s21, 17
	s_add_u32 s1, s1, s21
	s_lshl_b32 s1, s1, 1
	s_add_u32 s1, s1, 0x4001000
	s_add_u32 s30, s68, s1
	s_addc_u32 s31, s69, 0
	s_movk_i32 s20, 0x800
	s_branch .Ltc1_d159

; #define LAS __attribute__((address_space(3)))
; __device__ __forceinline__ unsigned cvt_pk_bf16(float lo, float hi) { unsigned r; asm("v_cvt_pk_bf16_f32 %0, %1, %2" : "=v"(r) : "v"(lo), "v"(hi)); return r; }
; __device__ __forceinline__ int opaque_tid() { int t = threadIdx.x; asm volatile("" : "+v"(t)); return t; }
; __device__ __forceinline__ void tconv_tile(LAS float* tile, const float* src, int ld, int k0, int n0, int mode, bf16_t* dst, int K) {
;     const int tid = opaque_tid();
; #pragma unroll
;     for (int it = 0; it < 2; ++it) { const int idx = tid + it * 512, kk = idx >> 4, n4 = (idx & 15) * 4, nn = n0 + n4; int oc = nn; bool valid = true;
;         if (mode == 1) { if (nn < 7680) oc = nn; else if (nn < 18944) oc = nn + 48; else if (nn < INW) oc = 7680 + (nn - 18944); else valid = false; }
;         f32x4 v = (f32x4){0.f, 0.f, 0.f, 0.f}; if (valid) v = *(const f32x4*)(src + (size_t)(k0 + kk) * ld + oc);
;         tile[kk * 65 + n4 + 0] = v[0]; tile[kk * 65 + n4 + 1] = v[1]; tile[kk * 65 + n4 + 2] = v[2]; tile[kk * 65 + n4 + 3] = v[3]; }
;     __syncthreads();
;     { const int n = tid >> 3, k8 = (tid & 7) * 8; float v[8];
; #pragma unroll
;         for (int e = 0; e < 8; ++e) v[e] = tile[(k8 + e) * 65 + n];
;         u32x4 w; w.x = cvt_pk_bf16(v[0], v[1]); w.y = cvt_pk_bf16(v[2], v[3]); w.z = cvt_pk_bf16(v[4], v[5]); w.w = cvt_pk_bf16(v[6], v[7]);
;         *(u32x4*)(dst + (size_t)(n0 + n) * K + k0 + k8) = w; }
;     __syncthreads();
; }
; __device__ __forceinline__ void prologue(LAS unsigned char* lds, const Ctx& P, int l) {
;     unsigned char* ws = P.ws; LAS float* tile = (LAS float*)lds;
;     const int tid = opaque_tid(), G = gridDim.x;
;     const int T_IN = 32 * 300, T_BR = 4 * 512, T_OUT = 1024, T_MEM = 1024, T_W1 = 256, T_WA = 64;
;     const int T_ALL = T_IN + T_BR + T_OUT + T_MEM + T_W1 + T_WA;
;     for (int t = blockIdx.x; t < T_ALL; t += G) {
;         int q = t;
;         if (q < T_IN) { const int kt = q & 31, ntl = q >> 5; tconv_tile(tile, P.in[3] + (size_t)l * DM * INW, INW, kt * 64, ntl * 64, 1, (bf16_t*)(ws + WS_WIN), DM); continue; }
.Ltc1_d166:
	v_mov_b32_e32 v78, 0
	v_mov_b32_e32 v79, 0
	v_mov_b32_e32 v80, 0
	v_mov_b32_e32 v81, 0
	v_mov_b32_e32 v82, 0
	v_mov_b32_e32 v83, 0
	v_mov_b32_e32 v84, 0
	v_mov_b32_e32 v85, 0
	v_mul_u32_u24_e32 v26, s28, v20
	v_add_lshl_u32 v26, v26, v21, 2
	s_lshl_b32 s0, s28, 7
	v_add_u32_e32 v27, s0, v26
	v_cmp_gt_i32_e32 vcc, s29, v21
	s_and_saveexec_b64 s[0:1], vcc
	global_load_dwordx4 v[78:81], v26, s[26:27]
	global_load_dwordx4 v[82:85], v27, s[26:27]
	s_mov_b64 exec, s[0:1]
	s_add_u32 s24, s24, s34
	s_cmpk_ge_u32 s25, 14016
	s_cbranch_scc1 .Ltc1_exit
	s_waitcnt vmcnt(15)
	v_add_u32_e32 v28, 16896, v22
	ds_write2_b32 v28, v86, v87 offset1:1
	ds_write2_b32 v28, v88, v89 offset0:2 offset1:3
	v_add_u32_e32 v28, 0x2080, v28
	ds_write2_b32 v28, v90, v91 offset1:1
	ds_write2_b32 v28, v92, v93 offset0:2 offset1:3
	s_mov_b32 s21, s25
	s_mov_b32 s0, s21
	s_cmpk_lt_u32 s0, 9600
	s_cbranch_scc0 .Ltc1_c180
	s_and_b32 s1, s0, 31
	s_lshl_b32 s1, s1, 6
	s_lshr_b32 s21, s0, 5
	s_lshl_b32 s21, s21, 17
	s_add_u32 s1, s1, s21
	s_lshl_b32 s1, s1, 1
	s_add_u32 s1, s1, 0x4001000
	s_add_u32 s30, s68, s1
	s_addc_u32 s31, s69, 0
	s_movk_i32 s20, 0x800
	s_branch .Ltc1_d179

; #define LAS __attribute__((address_space(3)))
; __device__ __forceinline__ unsigned cvt_pk_bf16(float lo, float hi) { unsigned r; asm("v_cvt_pk_bf16_f32 %0, %1, %2" : "=v"(r) : "v"(lo), "v"(hi)); return r; }
; __device__ __forceinline__ int opaque_tid() { int t = threadIdx.x; asm volatile("" : "+v"(t)); return t; }
; __device__ __forceinline__ void tconv_tile(LAS float* tile, const float* src, int ld, int k0, int n0, int mode, bf16_t* dst, int K) {
;     const int tid = opaque_tid();
; #pragma unroll
;     for (int it = 0; it < 2; ++it) { const int idx = tid + it * 512, kk = idx >> 4, n4 = (idx & 15) * 4, nn = n0 + n4; int oc = nn; bool valid = true;
;         if (mode == 1) { if (nn < 7680) oc = nn; else if (nn < 18944) oc = nn + 48; else if (nn < INW) oc = 7680 + (nn - 18944); else valid = false; }
;         f32x4 v = (f32x4){0.f, 0.f, 0.f, 0.f}; if (valid) v = *(const f32x4*)(src + (size_t)(k0 + kk) * ld + oc);
;         tile[kk * 65 + n4 + 0] = v[0]; tile[kk * 65 + n4 + 1] = v[1]; tile[kk * 65 + n4 + 2] = v[2]; tile[kk * 65 + n4 + 3] = v[3]; }
;     __syncthreads();
;     { const int n = tid >> 3, k8 = (tid & 7) * 8; float v[8];
; #pragma unroll
;         for (int e = 0; e < 8; ++e) v[e] = tile[(k8 + e) * 65 + n];
;         u32x4 w; w.x = cvt_pk_bf16(v[0], v[1]); w.y = cvt_pk_bf16(v[2], v[3]); w.z = cvt_pk_bf16(v[4], v[5]); w.w = cvt_pk_bf16(v[6], v[7]);
;         *(u32x4*)(dst + (size_t)(n0 + n) * K + k0 + k8) = w; }
;     __syncthreads();
; }
; __device__ __forceinline__ void prologue(LAS unsigned char* lds, const Ctx& P, int l) {
;     unsigned char* ws = P.ws; LAS float* tile = (LAS float*)lds;
;     const int tid = opaque_tid(), G = gridDim.x;
;     const int T_IN = 32 * 300, T_BR = 4 * 512, T_OUT = 1024, T_MEM = 1024, T_W1 = 256, T_WA = 64;
;     const int T_ALL = T_IN + T_BR + T_OUT + T_MEM + T_W1 + T_WA;
;     for (int t = blockIdx.x; t < T_ALL; t += G) {
;         int q = t;
;         if (q < T_IN) { const int kt = q & 31, ntl = q >> 5; tconv_tile(tile, P.in[3] + (size_t)l * DM * INW, INW, kt * 64, ntl * 64, 1, (bf16_t*)(ws + WS_WIN), DM); continue; }
.Ltc1_d186:
	v_mov_b32_e32 v86, 0
	v_mov_b32_e32 v87, 0
	v_mov_b32_e32 v88, 0
	v_mov_b32_e32 v89, 0
	v_mov_b32_e32 v90, 0
	v_mov_b32_e32 v91, 0
	v_mov_b32_e32 v92, 0
	v_mov_b32_e32 v93, 0
	v_mul_u32_u24_e32 v26, s28, v20
	v_add_lshl_u32 v26, v26, v21, 2
	s_lshl_b32 s0, s28, 7
	v_add_u32_e32 v27, s0, v26
	v_cmp_gt_i32_e32 vcc, s29, v21
	s_and_saveexec_b64 s[0:1], vcc
	global_load_dwordx4 v[86:89], v26, s[26:27]
	global_load_dwordx4 v[90:93], v27, s[26:27]
	s_mov_b64 exec, s[0:1]
	s_add_u32 s24, s24, s34
.Ltc1_loop:
	s_cmpk_ge_u32 s25, 14016
	s_cbranch_scc1 .Ltc1_exit
	s_waitcnt vmcnt(15)
	v_add_u32_e32 v28, 0, v22
	ds_write2_b32 v28, v34, v35 offset1:1
	ds_write2_b32 v28, v36, v37 offset0:2 offset1:3
	v_add_u32_e32 v28, 0x2080, v28
	ds_write2_b32 v28, v38, v39 offset1:1
	ds_write2_b32 v28, v40, v41 offset0:2 offset1:3
	s_mov_b32 s21, s25
	s_mov_b32 s0, s21
	s_cmpk_lt_u32 s0, 9600
	s_cbranch_scc0 .Ltc1_c200
	s_and_b32 s1, s0, 31
	s_lshl_b32 s1, s1, 6
	s_lshr_b32 s21, s0, 5
	s_lshl_b32 s21, s21, 17
	s_add_u32 s1, s1, s21
	s_lshl_b32 s1, s1, 1
	s_add_u32 s1, s1, 0x4001000
	s_add_u32 s30, s68, s1
	s_addc_u32 s31, s69, 0
	s_movk_i32 s20, 0x800
	s_branch .Ltc1_d199

; #define LAS __attribute__((address_space(3)))
; __device__ __forceinline__ unsigned cvt_pk_bf16(float lo, float hi) { unsigned r; asm("v_cvt_pk_bf16_f32 %0, %1, %2" : "=v"(r) : "v"(lo), "v"(hi)); return r; }
; __device__ __forceinline__ int opaque_tid() { int t = threadIdx.x; asm volatile("" : "+v"(t)); return t; }
; __device__ __forceinline__ void tconv_tile(LAS float* tile, const float* src, int ld, int k0, int n0, int mode, bf16_t* dst, int K) {
;     const int tid = opaque_tid();
; #pragma unroll
;     for (int it = 0; it < 2; ++it) { const int idx = tid + it * 512, kk = idx >> 4, n4 = (idx & 15) * 4, nn = n0 + n4; int oc = nn; bool valid = true;
;         if (mode == 1) { if (nn < 7680) oc = nn; else if (nn < 18944) oc = nn + 48; else if (nn < INW) oc = 7680 + (nn - 18944); else valid = false; }
;         f32x4 v = (f32x4){0.f, 0.f, 0.f, 0.f}; if (valid) v = *(const f32x4*)(src + (size_t)(k0 + kk) * ld + oc);
;         tile[kk * 65 + n4 + 0] = v[0]; tile[kk * 65 + n4 + 1] = v[1]; tile[kk * 65 + n4 + 2] = v[2]; tile[kk * 65 + n4 + 3] = v[3]; }
;     __syncthreads();
;     { const int n = tid >> 3, k8 = (tid & 7) * 8; float v[8];
; #pragma unroll
;         for (int e = 0; e < 8; ++e) v[e] = tile[(k8 + e) * 65 + n];
;         u32x4 w; w.x = cvt_pk_bf16(v[0], v[1]); w.y = cvt_pk_bf16(v[2], v[3]); w.z = cvt_pk_bf16(v[4], v[5]); w.w = cvt_pk_bf16(v[6], v[7]);
;         *(u32x4*)(dst + (size_t)(n0 + n) * K + k0 + k8) = w; }
;     __syncthreads();
; }
; __device__ __forceinline__ void prologue(LAS unsigned char* lds, const Ctx& P, int l) {
;     unsigned char* ws = P.ws; LAS float* tile = (LAS float*)lds;
;     const int tid = opaque_tid(), G = gridDim.x;
;     const int T_IN = 32 * 300, T_BR = 4 * 512, T_OUT = 1024, T_MEM = 1024, T_W1 = 256, T_WA = 64;
;     const int T_ALL = T_IN + T_BR + T_OUT + T_MEM + T_W1 + T_WA;
;     for (int t = blockIdx.x; t < T_ALL; t += G) {
;         int q = t;
;         if (q < T_IN) { const int kt = q & 31, ntl = q >> 5; tconv_tile(tile, P.in[3] + (size_t)l * DM * INW, INW, kt * 64, ntl * 64, 1, (bf16_t*)(ws + WS_WIN), DM); continue; }
.Ltc1_d206:
	v_mov_b32_e32 v34, 0
	v_mov_b32_e32 v35, 0
	v_mov_b32_e32 v36, 0
	v_mov_b32_e32 v37, 0
	v_mov_b32_e32 v38, 0
	v_mov_b32_e32 v39, 0
	v_mov_b32_e32 v40, 0
	v_mov_b32_e32 v41, 0
	v_mul_u32_u24_e32 v26, s28, v20
	v_add_lshl_u32 v26, v26, v21, 2
	s_lshl_b32 s0, s28, 7
	v_add_u32_e32 v27, s0, v26
	v_cmp_gt_i32_e32 vcc, s29, v21
	s_and_saveexec_b64 s[0:1], vcc
	global_load_dwordx4 v[34:37], v26, s[26:27]
	global_load_dwordx4 v[38:41], v27, s[26:27]
	s_mov_b64 exec, s[0:1]
	s_add_u32 s24, s24, s34
	s_cmpk_ge_u32 s25, 14016
	s_cbranch_scc1 .Ltc1_exit
	s_waitcnt vmcnt(15)
	v_add_u32_e32 v28, 16896, v22
	ds_write2_b32 v28, v42, v43 offset1:1
	ds_write2_b32 v28, v44, v45 offset0:2 offset1:3
	v_add_u32_e32 v28, 0x2080, v28
	ds_write2_b32 v28, v46, v47 offset1:1
	ds_write2_b32 v28, v48, v49 offset0:2 offset1:3
	s_mov_b32 s21, s25
	s_mov_b32 s0, s21
	s_cmpk_lt_u32 s0, 9600
	s_cbranch_scc0 .Ltc1_c220
	s_and_b32 s1, s0, 31
	s_lshl_b32 s1, s1, 6
	s_lshr_b32 s21, s0, 5
	s_lshl_b32 s21, s21, 17
	s_add_u32 s1, s1, s21
	s_lshl_b32 s1, s1, 1
	s_add_u32 s1, s1, 0x4001000
	s_add_u32 s30, s68, s1
	s_addc_u32 s31, s69, 0
	s_movk_i32 s20, 0x800
	s_branch .Ltc1_d219

; #define LAS __attribute__((address_space(3)))
; __device__ __forceinline__ unsigned cvt_pk_bf16(float lo, float hi) { unsigned r; asm("v_cvt_pk_bf16_f32 %0, %1, %2" : "=v"(r) : "v"(lo), "v"(hi)); return r; }
; __device__ __forceinline__ int opaque_tid() { int t = threadIdx.x; asm volatile("" : "+v"(t)); return t; }
; __device__ __forceinline__ void tconv_tile(LAS float* tile, const float* src, int ld, int k0, int n0, int mode, bf16_t* dst, int K) {
;     const int tid = opaque_tid();
; #pragma unroll
;     for (int it = 0; it < 2; ++it) { const int idx = tid + it * 512, kk = idx >> 4, n4 = (idx & 15) * 4, nn = n0 + n4; int oc = nn; bool valid = true;
;         if (mode == 1) { if (nn < 7680) oc = nn; else if (nn < 18944) oc = nn + 48; else if (nn < INW) oc = 7680 + (nn - 18944); else valid = false; }
;         f32x4 v = (f32x4){0.f, 0.f, 0.f, 0.f}; if (valid) v = *(const f32x4*)(src + (size_t)(k0 + kk) * ld + oc);
;         tile[kk * 65 + n4 + 0] = v[0]; tile[kk * 65 + n4 + 1] = v[1]; tile[kk * 65 + n4 + 2] = v[2]; tile[kk * 65 + n4 + 3] = v[3]; }
;     __syncthreads();
;     { const int n = tid >> 3, k8 = (tid & 7) * 8; float v[8];
; #pragma unroll
;         for (int e = 0; e < 8; ++e) v[e] = tile[(k8 + e) * 65 + n];
;         u32x4 w; w.x = cvt_pk_bf16(v[0], v[1]); w.y = cvt_pk_bf16(v[2], v[3]); w.z = cvt_pk_bf16(v[4], v[5]); w.w = cvt_pk_bf16(v[6], v[7]);
;         *(u32x4*)(dst + (size_t)(n0 + n) * K + k0 + k8) = w; }
;     __syncthreads();
; }
; __device__ __forceinline__ void prologue(LAS unsigned char* lds, const Ctx& P, int l) {
;     unsigned char* ws = P.ws; LAS float* tile = (LAS float*)lds;
;     const int tid = opaque_tid(), G = gridDim.x;
;     const int T_IN = 32 * 300, T_BR = 4 * 512, T_OUT = 1024, T_MEM = 1024, T_W1 = 256, T_WA = 64;
;     const int T_ALL = T_IN + T_BR + T_OUT + T_MEM + T_W1 + T_WA;
;     for (int t = blockIdx.x; t < T_ALL; t += G) {
;         int q = t;
;         if (q < T_IN) { const int kt = q & 31, ntl = q >> 5; tconv_tile(tile, P.in[3] + (size_t)l * DM * INW, INW, kt * 64, ntl * 64, 1, (bf16_t*)(ws + WS_WIN), DM); continue; }
.Ltc1_d226:
	v_mov_b32_e32 v42, 0
	v_mov_b32_e32 v43, 0
	v_mov_b32_e32 v44, 0
	v_mov_b32_e32 v45, 0
	v_mov_b32_e32 v46, 0
	v_mov_b32_e32 v47, 0
	v_mov_b32_e32 v48, 0
	v_mov_b32_e32 v49, 0
	v_mul_u32_u24_e32 v26, s28, v20
	v_add_lshl_u32 v26, v26, v21, 2
	s_lshl_b32 s0, s28, 7
	v_add_u32_e32 v27, s0, v26
	v_cmp_gt_i32_e32 vcc, s29, v21
	s_and_saveexec_b64 s[0:1], vcc
	global_load_dwordx4 v[42:45], v26, s[26:27]
	global_load_dwordx4 v[46:49], v27, s[26:27]
	s_mov_b64 exec, s[0:1]
	s_add_u32 s24, s24, s34
	s_cmpk_ge_u32 s25, 14016
	s_cbranch_scc1 .Ltc1_exit
	s_waitcnt vmcnt(15)
	v_add_u32_e32 v28, 0, v22
	ds_write2_b32 v28, v50, v51 offset1:1
	ds_write2_b32 v28, v52, v53 offset0:2 offset1:3
	v_add_u32_e32 v28, 0x2080, v28
	ds_write2_b32 v28, v54, v55 offset1:1
	ds_write2_b32 v28, v56, v57 offset0:2 offset1:3
	s_mov_b32 s21, s25
	s_mov_b32 s0, s21
	s_cmpk_lt_u32 s0, 9600
	s_cbranch_scc0 .Ltc1_c240
	s_and_b32 s1, s0, 31
	s_lshl_b32 s1, s1, 6
	s_lshr_b32 s21, s0, 5
	s_lshl_b32 s21, s21, 17
	s_add_u32 s1, s1, s21
	s_lshl_b32 s1, s1, 1
	s_add_u32 s1, s1, 0x4001000
	s_add_u32 s30, s68, s1
	s_addc_u32 s31, s69, 0
	s_movk_i32 s20, 0x800
	s_branch .Ltc1_d239

; #define LAS __attribute__((address_space(3)))
; __device__ __forceinline__ unsigned cvt_pk_bf16(float lo, float hi) { unsigned r; asm("v_cvt_pk_bf16_f32 %0, %1, %2" : "=v"(r) : "v"(lo), "v"(hi)); return r; }
; __device__ __forceinline__ int opaque_tid() { int t = threadIdx.x; asm volatile("" : "+v"(t)); return t; }
; __device__ __forceinline__ void tconv_tile(LAS float* tile, const float* src, int ld, int k0, int n0, int mode, bf16_t* dst, int K) {
;     const int tid = opaque_tid();
; #pragma unroll
;     for (int it = 0; it < 2; ++it) { const int idx = tid + it * 512, kk = idx >> 4, n4 = (idx & 15) * 4, nn = n0 + n4; int oc = nn; bool valid = true;
;         if (mode == 1) { if (nn < 7680) oc = nn; else if (nn < 18944) oc = nn + 48; else if (nn < INW) oc = 7680 + (nn - 18944); else valid = false; }
;         f32x4 v = (f32x4){0.f, 0.f, 0.f, 0.f}; if (valid) v = *(const f32x4*)(src + (size_t)(k0 + kk) * ld + oc);
;         tile[kk * 65 + n4 + 0] = v[0]; tile[kk * 65 + n4 + 1] = v[1]; tile[kk * 65 + n4 + 2] = v[2]; tile[kk * 65 + n4 + 3] = v[3]; }
;     __syncthreads();
;     { const int n = tid >> 3, k8 = (tid & 7) * 8; float v[8];
; #pragma unroll
;         for (int e = 0; e < 8; ++e) v[e] = tile[(k8 + e) * 65 + n];
;         u32x4 w; w.x = cvt_pk_bf16(v[0], v[1]); w.y = cvt_pk_bf16(v[2], v[3]); w.z = cvt_pk_bf16(v[4], v[5]); w.w = cvt_pk_bf16(v[6], v[7]);
;         *(u32x4*)(dst + (size_t)(n0 + n) * K + k0 + k8) = w; }
;     __syncthreads();
; }
; __device__ __forceinline__ void prologue(LAS unsigned char* lds, const Ctx& P, int l) {
;     unsigned char* ws = P.ws; LAS float* tile = (LAS float*)lds;
;     const int tid = opaque_tid(), G = gridDim.x;
;     const int T_IN = 32 * 300, T_BR = 4 * 512, T_OUT = 1024, T_MEM = 1024, T_W1 = 256, T_WA = 64;
;     const int T_ALL = T_IN + T_BR + T_OUT + T_MEM + T_W1 + T_WA;
;     for (int t = blockIdx.x; t < T_ALL; t += G) {
;         int q = t;
;         if (q < T_IN) { const int kt = q & 31, ntl = q >> 5; tconv_tile(tile, P.in[3] + (size_t)l * DM * INW, INW, kt * 64, ntl * 64, 1, (bf16_t*)(ws + WS_WIN), DM); continue; }
.Ltc1_d246:
	v_mov_b32_e32 v50, 0
	v_mov_b32_e32 v51, 0
	v_mov_b32_e32 v52, 0
	v_mov_b32_e32 v53, 0
	v_mov_b32_e32 v54, 0
	v_mov_b32_e32 v55, 0
	v_mov_b32_e32 v56, 0
	v_mov_b32_e32 v57, 0
	v_mul_u32_u24_e32 v26, s28, v20
	v_add_lshl_u32 v26, v26, v21, 2
	s_lshl_b32 s0, s28, 7
	v_add_u32_e32 v27, s0, v26
	v_cmp_gt_i32_e32 vcc, s29, v21
	s_and_saveexec_b64 s[0:1], vcc
	global_load_dwordx4 v[50:53], v26, s[26:27]
	global_load_dwordx4 v[54:57], v27, s[26:27]
	s_mov_b64 exec, s[0:1]
	s_add_u32 s24, s24, s34
	s_cmpk_ge_u32 s25, 14016
	s_cbranch_scc1 .Ltc1_exit
	s_waitcnt vmcnt(15)
	v_add_u32_e32 v28, 16896, v22
	ds_write2_b32 v28, v58, v59 offset1:1
	ds_write2_b32 v28, v60, v61 offset0:2 offset1:3
	v_add_u32_e32 v28, 0x2080, v28
	ds_write2_b32 v28, v62, v63 offset1:1
	ds_write2_b32 v28, v64, v65 offset0:2 offset1:3
	s_mov_b32 s21, s25
	s_mov_b32 s0, s21
	s_cmpk_lt_u32 s0, 9600
	s_cbranch_scc0 .Ltc1_c260
	s_and_b32 s1, s0, 31
	s_lshl_b32 s1, s1, 6
	s_lshr_b32 s21, s0, 5
	s_lshl_b32 s21, s21, 17
	s_add_u32 s1, s1, s21
	s_lshl_b32 s1, s1, 1
	s_add_u32 s1, s1, 0x4001000
	s_add_u32 s30, s68, s1
	s_addc_u32 s31, s69, 0
	s_movk_i32 s20, 0x800
	s_branch .Ltc1_d259

; #define LAS __attribute__((address_space(3)))
; __device__ __forceinline__ unsigned cvt_pk_bf16(float lo, float hi) { unsigned r; asm("v_cvt_pk_bf16_f32 %0, %1, %2" : "=v"(r) : "v"(lo), "v"(hi)); return r; }
; __device__ __forceinline__ int opaque_tid() { int t = threadIdx.x; asm volatile("" : "+v"(t)); return t; }
; __device__ __forceinline__ void tconv_tile(LAS float* tile, const float* src, int ld, int k0, int n0, int mode, bf16_t* dst, int K) {
;     const int tid = opaque_tid();
; #pragma unroll
;     for (int it = 0; it < 2; ++it) { const int idx = tid + it * 512, kk = idx >> 4, n4 = (idx & 15) * 4, nn = n0 + n4; int oc = nn; bool valid = true;
;         if (mode == 1) { if (nn < 7680) oc = nn; else if (nn < 18944) oc = nn + 48; else if (nn < INW) oc = 7680 + (nn - 18944); else valid = false; }
;         f32x4 v = (f32x4){0.f, 0.f, 0.f, 0.f}; if (valid) v = *(const f32x4*)(src + (size_t)(k0 + kk) * ld + oc);
;         tile[kk * 65 + n4 + 0] = v[0]; tile[kk * 65 + n4 + 1] = v[1]; tile[kk * 65 + n4 + 2] = v[2]; tile[kk * 65 + n4 + 3] = v[3]; }
;     __syncthreads();
;     { const int n = tid >> 3, k8 = (tid & 7) * 8; float v[8];
; #pragma unroll
;         for (int e = 0; e < 8; ++e) v[e] = tile[(k8 + e) * 65 + n];
;         u32x4 w; w.x = cvt_pk_bf16(v[0], v[1]); w.y = cvt_pk_bf16(v[2], v[3]); w.z = cvt_pk_bf16(v[4], v[5]); w.w = cvt_pk_bf16(v[6], v[7]);
;         *(u32x4*)(dst + (size_t)(n0 + n) * K + k0 + k8) = w; }
;     __syncthreads();
; }
; __device__ __forceinline__ void prologue(LAS unsigned char* lds, const Ctx& P, int l) {
;     unsigned char* ws = P.ws; LAS float* tile = (LAS float*)lds;
;     const int tid = opaque_tid(), G = gridDim.x;
;     const int T_IN = 32 * 300, T_BR = 4 * 512, T_OUT = 1024, T_MEM = 1024, T_W1 = 256, T_WA = 64;
;     const int T_ALL = T_IN + T_BR + T_OUT + T_MEM + T_W1 + T_WA;
;     for (int t = blockIdx.x; t < T_ALL; t += G) {
;         int q = t;
;         if (q < T_IN) { const int kt = q & 31, ntl = q >> 5; tconv_tile(tile, P.in[3] + (size_t)l * DM * INW, INW, kt * 64, ntl * 64, 1, (bf16_t*)(ws + WS_WIN), DM); continue; }
.Ltc1_d266:
	v_mov_b32_e32 v58, 0
	v_mov_b32_e32 v59, 0
	v_mov_b32_e32 v60, 0
	v_mov_b32_e32 v61, 0
	v_mov_b32_e32 v62, 0
	v_mov_b32_e32 v63, 0
	v_mov_b32_e32 v64, 0
	v_mov_b32_e32 v65, 0
	v_mul_u32_u24_e32 v26, s28, v20
	v_add_lshl_u32 v26, v26, v21, 2
	s_lshl_b32 s0, s28, 7
	v_add_u32_e32 v27, s0, v26
	v_cmp_gt_i32_e32 vcc, s29, v21
	s_and_saveexec_b64 s[0:1], vcc
	global_load_dwordx4 v[58:61], v26, s[26:27]
	global_load_dwordx4 v[62:65], v27, s[26:27]
	s_mov_b64 exec, s[0:1]
	s_add_u32 s24, s24, s34
	s_cmpk_ge_u32 s25, 14016
	s_cbranch_scc1 .Ltc1_exit
	s_waitcnt vmcnt(15)
	v_add_u32_e32 v28, 0, v22
	ds_write2_b32 v28, v78, v79 offset1:1
	ds_write2_b32 v28, v80, v81 offset0:2 offset1:3
	v_add_u32_e32 v28, 0x2080, v28
	ds_write2_b32 v28, v82, v83 offset1:1
	ds_write2_b32 v28, v84, v85 offset0:2 offset1:3
	s_mov_b32 s21, s25
	s_mov_b32 s0, s21
	s_cmpk_lt_u32 s0, 9600
	s_cbranch_scc0 .Ltc1_c280
	s_and_b32 s1, s0, 31
	s_lshl_b32 s1, s1, 6
	s_lshr_b32 s21, s0, 5
	s_lshl_b32 s21, s21, 17
	s_add_u32 s1, s1, s21
	s_lshl_b32 s1, s1, 1
	s_add_u32 s1, s1, 0x4001000
	s_add_u32 s30, s68, s1
	s_addc_u32 s31, s69, 0
	s_movk_i32 s20, 0x800
	s_branch .Ltc1_d279

; #define LAS __attribute__((address_space(3)))
; __device__ __forceinline__ unsigned cvt_pk_bf16(float lo, float hi) { unsigned r; asm("v_cvt_pk_bf16_f32 %0, %1, %2" : "=v"(r) : "v"(lo), "v"(hi)); return r; }
; __device__ __forceinline__ int opaque_tid() { int t = threadIdx.x; asm volatile("" : "+v"(t)); return t; }
; __device__ __forceinline__ void tconv_tile(LAS float* tile, const float* src, int ld, int k0, int n0, int mode, bf16_t* dst, int K) {
;     const int tid = opaque_tid();
; #pragma unroll
;     for (int it = 0; it < 2; ++it) { const int idx = tid + it * 512, kk = idx >> 4, n4 = (idx & 15) * 4, nn = n0 + n4; int oc = nn; bool valid = true;
;         if (mode == 1) { if (nn < 7680) oc = nn; else if (nn < 18944) oc = nn + 48; else if (nn < INW) oc = 7680 + (nn - 18944); else valid = false; }
;         f32x4 v = (f32x4){0.f, 0.f, 0.f, 0.f}; if (valid) v = *(const f32x4*)(src + (size_t)(k0 + kk) * ld + oc);
;         tile[kk * 65 + n4 + 0] = v[0]; tile[kk * 65 + n4 + 1] = v[1]; tile[kk * 65 + n4 + 2] = v[2]; tile[kk * 65 + n4 + 3] = v[3]; }
;     __syncthreads();
;     { const int n = tid >> 3, k8 = (tid & 7) * 8; float v[8];
; #pragma unroll
;         for (int e = 0; e < 8; ++e) v[e] = tile[(k8 + e) * 65 + n];
;         u32x4 w; w.x = cvt_pk_bf16(v[0], v[1]); w.y = cvt_pk_bf16(v[2], v[3]); w.z = cvt_pk_bf16(v[4], v[5]); w.w = cvt_pk_bf16(v[6], v[7]);
;         *(u32x4*)(dst + (size_t)(n0 + n) * K + k0 + k8) = w; }
;     __syncthreads();
; }
; __device__ __forceinline__ void prologue(LAS unsigned char* lds, const Ctx& P, int l) {
;     unsigned char* ws = P.ws; LAS float* tile = (LAS float*)lds;
;     const int tid = opaque_tid(), G = gridDim.x;
;     const int T_IN = 32 * 300, T_BR = 4 * 512, T_OUT = 1024, T_MEM = 1024, T_W1 = 256, T_WA = 64;
;     const int T_ALL = T_IN + T_BR + T_OUT + T_MEM + T_W1 + T_WA;
;     for (int t = blockIdx.x; t < T_ALL; t += G) {
;         int q = t;
;         if (q < T_IN) { const int kt = q & 31, ntl = q >> 5; tconv_tile(tile, P.in[3] + (size_t)l * DM * INW, INW, kt * 64, ntl * 64, 1, (bf16_t*)(ws + WS_WIN), DM); continue; }
.Ltc1_d306:
	v_mov_b32_e32 v86, 0
	v_mov_b32_e32 v87, 0
	v_mov_b32_e32 v88, 0
	v_mov_b32_e32 v89, 0
	v_mov_b32_e32 v90, 0
	v_mov_b32_e32 v91, 0
	v_mov_b32_e32 v92, 0
	v_mov_b32_e32 v93, 0
	v_mul_u32_u24_e32 v26, s28, v20
	v_add_lshl_u32 v26, v26, v21, 2
	s_lshl_b32 s0, s28, 7
	v_add_u32_e32 v27, s0, v26
	v_cmp_gt_i32_e32 vcc, s29, v21
	s_and_saveexec_b64 s[0:1], vcc
	global_load_dwordx4 v[86:89], v26, s[26:27]
	global_load_dwordx4 v[90:93], v27, s[26:27]
	s_mov_b64 exec, s[0:1]
	s_add_u32 s24, s24, s34
	s_branch .Ltc1_loop
